# combined: scan LDS hoist + 12 movs folded into op_sel, attention flags via ds ops, 4a/4b epilogue load prefetch, nt stores in ffn gate/up epilogue
# speedup vs baseline: 1.0092x; 1.0092x over previous
; __device__ __forceinline__ float dot4(const f32x4& a, const f32x4& b) {
;     f32x2 t = __builtin_shufflevector(a, a, 0, 1) * __builtin_shufflevector(b, b, 0, 1);
;     t = __builtin_shufflevector(a, a, 2, 3) * __builtin_shufflevector(b, b, 2, 3) + t;
;     return t[0] + t[1];
; }
; __device__ __forceinline__ void scan_unit(const Params& p, int unit) {
;     ...
;         for (int c = 0; c < SC_NC; ++c) {
;             const float* buf = (const float*)(smem + (c & 1) * SC_BUF);
;             float* yb = (float*)(smem + SC_YOFF + (c & 1) * SC_YBUF);
;             const float* bp = buf + sub * 4;
;     ...
;             f32x4 r1 = SC_LD(0, 0), w1 = SC_LD(1, 0), k1 = SC_LD(2, 0), q1 = SC_LD(3, 0), n1 = SC_LD(4, 0);
;             f32x4 r2 = SC_LD(0, 1), w2 = SC_LD(1, 1), k2 = SC_LD(2, 1), g2 = SC_LD(3, 1), n2 = SC_LD(4, 1);
;             float v1 = buf[SC_VOFF + rl], v2 = buf[SC_VOFF + 16 + rl];
;             f32x2 cf = *(const f32x2*)(buf + SC_COFF);
; #pragma unroll
;             for (int pr = 0; pr < SC_TC / 2; ++pr) {
;                 const int sn = 2 * pr + 2;
;                 const f32x4 r1n = SC_LD(0, sn), w1n = SC_LD(1, sn), k1n = SC_LD(2, sn), q1n = SC_LD(3, sn), n1n = SC_LD(4, sn);
;                 const f32x4 r2n = SC_LD(0, sn + 1), w2n = SC_LD(1, sn + 1), k2n = SC_LD(2, sn + 1), g2n = SC_LD(3, sn + 1), n2n = SC_LD(4, sn + 1);
;                 const float v1n = buf[SC_VOFF + sn * 16 + rl], v2n = buf[SC_VOFF + (sn + 1) * 16 + rl];
;                 const f32x2 cfn = *(const f32x2*)(buf + SC_COFF + (pr + 1) * 2);
;                 __builtin_amdgcn_sched_barrier(0x7);
;                 float d1 = dot4(S, q1), e2 = dot4(S, g2);
;                 const f32x4 t1 = S * w1 + v1 * k1;
;                 reduce16x2(d1, e2);
;                 const float d2 = e2 + v1 * cf[0] - d1 * cf[1];
;                 const f32x4 S1 = t1 + d1 * n1;
;                 const f32x4 S2 = (S1 * w2 + v2 * k2) + d2 * n2;
;                 float y1 = dot4(S1, r1), y2 = dot4(S2, r2);
;                 y1 += dppf<0xB1>(y1); y2 += dppf<0xB1>(y2);
;                 float yz = odd_lane ? y2 : y1;
;                 yz += dppf<0x122>(yz); yz += dppf<0x124>(yz); yz += dppf<0x128>(yz);
;                 yb[(2 * pr) * 16 + yoff] = yz;
;                 S = S2;
;                 r1 = r1n; w1 = w1n; k1 = k1n; q1 = q1n; n1 = n1n; r2 = r2n; w2 = w2n; k2 = k2n; g2 = g2n; n2 = n2n; v1 = v1n; v2 = v2n; cf = cfn;
.LBB0_786:
	s_and_b32 s5, s4, 1
	s_mul_i32 s6, s5, 0xa880
	v_lshl_add_u32 v6, s5, 11, v5
	s_add_i32 s5, s6, 0
	v_lshl_add_u32 v9, v169, 2, s5
	v_mov_b32_e32 v7, s5
	v_lshl_add_u32 v8, v4, 2, s5
	v_add_u32_e32 v129, 0xa000, v9
	ds_read_b128 v[10:13], v8
	ds_read_b128 v[14:17], v8 offset:256
	ds_read_b128 v[18:21], v8 offset:8192
	ds_read_b128 v[22:25], v8 offset:8448
	ds_read_b128 v[26:29], v8 offset:16384
	ds_read_b128 v[30:33], v8 offset:16640
	ds_read_b128 v[34:37], v8 offset:24576
	ds_read_b128 v[38:41], v8 offset:24832
	ds_read_b128 v[42:45], v8 offset:32768
	ds_read_b128 v[46:49], v8 offset:33024
	ds_read_b128 v[50:53], v7 offset:43008
	ds_read_b128 v[54:57], v8 offset:512
	ds_read_b128 v[58:61], v8 offset:768
	ds_read_b128 v[62:65], v8 offset:8704
	ds_read_b128 v[66:69], v8 offset:8960
	ds_read_b128 v[70:73], v8 offset:16896
	ds_read_b128 v[74:77], v8 offset:17152
	ds_read_b128 v[78:81], v8 offset:25088
	ds_read_b128 v[82:85], v8 offset:25344
	ds_read_b128 v[86:89], v8 offset:33280
	ds_read_b128 v[90:93], v8 offset:33536
	ds_read2_b32 v[126:127], v129 offset1:16
	ds_read2_b32 v[142:143], v129 offset0:32 offset1:48
	s_waitcnt lgkmcnt(14)
	v_pk_mul_f32 v[36:37], v[2:3], v[36:37]
	v_pk_mul_f32 v[40:41], v[2:3], v[40:41]
	v_pk_fma_f32 v[34:35], v[0:1], v[34:35], v[36:37]
	v_pk_fma_f32 v[36:37], v[0:1], v[38:39], v[40:41]
	s_waitcnt lgkmcnt(1)
	ds_read_b128 v[94:97], v8 offset:1024
	ds_read_b128 v[98:101], v8 offset:1280
	ds_read_b128 v[102:105], v8 offset:9216
	ds_read_b128 v[106:109], v8 offset:9472
	ds_read_b128 v[110:113], v8 offset:17408
	ds_read_b128 v[114:117], v8 offset:17664
	ds_read_b128 v[118:121], v8 offset:25600
	ds_read_b128 v[122:125], v8 offset:25856
	ds_read_b128 v[134:137], v8 offset:33792
	ds_read_b128 v[138:141], v8 offset:34048
	ds_read2_b32 v[144:145], v129 offset0:64 offset1:80
	ds_read_b64 v[146:147], v7 offset:43024
	v_pk_mul_f32 v[26:27], v[26:27], v[126:127] op_sel_hi:[1,0]
	v_add_f32_e32 v34, v34, v35
	v_add_f32_e32 v35, v36, v37
	v_pk_fma_f32 v[0:1], v[0:1], v[18:19], v[26:27]
	v_add_f32_dpp v18, v34, v34 quad_perm:[1,0,3,2] row_mask:0xf bank_mask:0xf bound_ctrl:1
	v_add_f32_dpp v19, v35, v35 quad_perm:[1,0,3,2] row_mask:0xf bank_mask:0xf bound_ctrl:1
	v_pk_mul_f32 v[28:29], v[28:29], v[126:127] op_sel_hi:[1,0]
	v_add_f32_dpp v18, v18, v18 quad_perm:[2,3,0,1] row_mask:0xf bank_mask:0xf bound_ctrl:1
	v_add_f32_dpp v19, v19, v19 quad_perm:[2,3,0,1] row_mask:0xf bank_mask:0xf bound_ctrl:1
	v_mov_b32_e32 v38, v127
	v_add_f32_dpp v18, v18, v18 row_half_mirror row_mask:0xf bank_mask:0xf bound_ctrl:1
	v_add_f32_dpp v19, v19, v19 row_half_mirror row_mask:0xf bank_mask:0xf bound_ctrl:1
	v_pk_fma_f32 v[2:3], v[2:3], v[20:21], v[28:29]
	v_add_f32_dpp v127, v18, v18 row_mirror row_mask:0xf bank_mask:0xf bound_ctrl:1
	v_add_f32_dpp v21, v19, v19 row_mirror row_mask:0xf bank_mask:0xf bound_ctrl:1
	v_pk_mul_f32 v[18:19], v[126:127], v[50:51]
	v_pk_fma_f32 v[2:3], v[44:45], v[126:127], v[2:3] op_sel:[0,1,0]
	v_pk_fma_f32 v[0:1], v[42:43], v[126:127], v[0:1] op_sel:[0,1,0]
	v_add_f32_e32 v18, v18, v21
	v_pk_mul_f32 v[20:21], v[22:23], v[0:1]
	v_pk_mul_f32 v[22:23], v[24:25], v[2:3]
	v_pk_mul_f32 v[2:3], v[12:13], v[2:3]
	v_sub_f32_e32 v18, v18, v19
	v_pk_fma_f32 v[12:13], v[32:33], v[38:39], v[22:23] op_sel_hi:[1,0,1]
	v_pk_fma_f32 v[0:1], v[10:11], v[0:1], v[2:3]
	v_pk_fma_f32 v[20:21], v[30:31], v[38:39], v[20:21] op_sel_hi:[1,0,1]
	v_pk_fma_f32 v[10:11], v[48:49], v[18:19], v[12:13] op_sel_hi:[1,0,1]
	v_add_f32_e32 v12, v0, v1
	v_pk_fma_f32 v[2:3], v[46:47], v[18:19], v[20:21] op_sel_hi:[1,0,1]
	v_pk_mul_f32 v[0:1], v[16:17], v[10:11]
	v_add_f32_dpp v20, v12, v12 quad_perm:[1,0,3,2] row_mask:0xf bank_mask:0xf bound_ctrl:1
	v_pk_mul_f32 v[12:13], v[80:81], v[10:11]
	v_pk_mul_f32 v[16:17], v[84:85], v[10:11]
	v_pk_fma_f32 v[0:1], v[14:15], v[2:3], v[0:1]
	v_pk_fma_f32 v[12:13], v[78:79], v[2:3], v[12:13]
	v_pk_mul_f32 v[18:19], v[62:63], v[2:3]
	v_pk_fma_f32 v[2:3], v[82:83], v[2:3], v[16:17]
	v_add_f32_e32 v0, v0, v1
	v_add_f32_e32 v1, v12, v13
	v_add_f32_e32 v2, v2, v3
	v_add_f32_dpp v0, v0, v0 quad_perm:[1,0,3,2] row_mask:0xf bank_mask:0xf bound_ctrl:1
	v_add_f32_dpp v1, v1, v1 quad_perm:[1,0,3,2] row_mask:0xf bank_mask:0xf bound_ctrl:1
	v_add_f32_dpp v2, v2, v2 quad_perm:[1,0,3,2] row_mask:0xf bank_mask:0xf bound_ctrl:1
	v_cndmask_b32_e32 v0, v0, v20, vcc
	v_add_f32_dpp v1, v1, v1 quad_perm:[2,3,0,1] row_mask:0xf bank_mask:0xf bound_ctrl:1
	v_add_f32_dpp v2, v2, v2 quad_perm:[2,3,0,1] row_mask:0xf bank_mask:0xf bound_ctrl:1
	v_add_f32_dpp v0, v0, v0 row_ror:2 row_mask:0xf bank_mask:0xf bound_ctrl:1
	v_add_f32_dpp v1, v1, v1 row_half_mirror row_mask:0xf bank_mask:0xf bound_ctrl:1
	v_pk_mul_f32 v[10:11], v[64:65], v[10:11]
	v_add_f32_dpp v2, v2, v2 row_half_mirror row_mask:0xf bank_mask:0xf bound_ctrl:1
	v_add_f32_dpp v0, v0, v0 row_ror:4 row_mask:0xf bank_mask:0xf bound_ctrl:1
	v_add_f32_dpp v41, v1, v1 row_mirror row_mask:0xf bank_mask:0xf bound_ctrl:1
	s_waitcnt lgkmcnt(12)
	v_mov_b32_e32 v40, v142
	v_pk_fma_f32 v[14:15], v[70:71], v[142:143], v[18:19] op_sel_hi:[1,0,1]
	v_pk_fma_f32 v[10:11], v[72:73], v[142:143], v[10:11] op_sel_hi:[1,0,1]
	v_add_f32_dpp v1, v2, v2 row_mirror row_mask:0xf bank_mask:0xf bound_ctrl:1
	v_add_f32_dpp v2, v0, v0 row_ror:8 row_mask:0xf bank_mask:0xf bound_ctrl:1
	v_pk_mul_f32 v[46:47], v[40:41], v[52:53]
	v_pk_fma_f32 v[48:49], v[88:89], v[40:41], v[10:11] op_sel:[0,1,0]
	v_pk_fma_f32 v[50:51], v[86:87], v[40:41], v[14:15] op_sel:[0,1,0]
	v_mov_b32_e32 v148, v143
	v_add_f32_e32 v46, v46, v1
	v_pk_mul_f32 v[52:53], v[66:67], v[50:51]
	v_pk_mul_f32 v[62:63], v[68:69], v[48:49]
	v_pk_mul_f32 v[48:49], v[56:57], v[48:49]
	v_sub_f32_e32 v46, v46, v47
	v_pk_fma_f32 v[56:57], v[76:77], v[148:149], v[62:63] op_sel_hi:[1,0,1]
	v_pk_fma_f32 v[52:53], v[74:75], v[148:149], v[52:53] op_sel_hi:[1,0,1]
	v_pk_fma_f32 v[48:49], v[54:55], v[50:51], v[48:49]
	v_pk_fma_f32 v[50:51], v[90:91], v[46:47], v[52:53] op_sel_hi:[1,0,1]
	v_pk_fma_f32 v[46:47], v[92:93], v[46:47], v[56:57] op_sel_hi:[1,0,1]
	v_add_f32_e32 v52, v48, v49
	v_pk_mul_f32 v[48:49], v[60:61], v[46:47]
	v_add_f32_dpp v60, v52, v52 quad_perm:[1,0,3,2] row_mask:0xf bank_mask:0xf bound_ctrl:1
	s_waitcnt lgkmcnt(5)
; template <int CTRL> __device__ __forceinline__ float dppf(float x) { return __builtin_bit_cast(float, __builtin_amdgcn_mov_dpp(__builtin_bit_cast(int, x), CTRL, 0xf, 0xf, true)); }
; __device__ __forceinline__ float dot4(const f32x4& a, const f32x4& b) {
;     f32x2 t = __builtin_shufflevector(a, a, 0, 1) * __builtin_shufflevector(b, b, 0, 1);
;     t = __builtin_shufflevector(a, a, 2, 3) * __builtin_shufflevector(b, b, 2, 3) + t;
;     return t[0] + t[1];
; }
; __device__ __forceinline__ void reduce16x2(float& a, float& b) {
;     a += dppf<0xB1>(a); b += dppf<0xB1>(b); a += dppf<0x4E>(a); b += dppf<0x4E>(b);
;     a += dppf<0x141>(a); b += dppf<0x141>(b); a += dppf<0x140>(a); b += dppf<0x140>(b);
; }
; __device__ __forceinline__ void scan_unit(const Params& p, int unit) {
;     ...
;             for (int pr = 0; pr < SC_TC / 2; ++pr) {
;                 const int sn = 2 * pr + 2;
;                 const f32x4 r1n = SC_LD(0, sn), w1n = SC_LD(1, sn), k1n = SC_LD(2, sn), q1n = SC_LD(3, sn), n1n = SC_LD(4, sn);
;                 const f32x4 r2n = SC_LD(0, sn + 1), w2n = SC_LD(1, sn + 1), k2n = SC_LD(2, sn + 1), g2n = SC_LD(3, sn + 1), n2n = SC_LD(4, sn + 1);
;                 const float v1n = buf[SC_VOFF + sn * 16 + rl], v2n = buf[SC_VOFF + (sn + 1) * 16 + rl];
;                 const f32x2 cfn = *(const f32x2*)(buf + SC_COFF + (pr + 1) * 2);
;                 __builtin_amdgcn_sched_barrier(0x7);
;                 float d1 = dot4(S, q1), e2 = dot4(S, g2);
;                 const f32x4 t1 = S * w1 + v1 * k1;
;                 reduce16x2(d1, e2);
;                 const float d2 = e2 + v1 * cf[0] - d1 * cf[1];
;                 const f32x4 S1 = t1 + d1 * n1;
;                 const f32x4 S2 = (S1 * w2 + v2 * k2) + d2 * n2;
;                 float y1 = dot4(S1, r1), y2 = dot4(S2, r2);
;                 y1 += dppf<0xB1>(y1); y2 += dppf<0xB1>(y2);
;                 float yz = odd_lane ? y2 : y1;
;                 yz += dppf<0x122>(yz); yz += dppf<0x124>(yz); yz += dppf<0x128>(yz);
;                 yb[(2 * pr) * 16 + yoff] = yz;
;                 S = S2;
;                 r1 = r1n; w1 = w1n; k1 = k1n; q1 = q1n; n1 = n1n; r2 = r2n; w2 = w2n; k2 = k2n; g2 = g2n; n2 = n2n; v1 = v1n; v2 = v2n; cf = cfn;
	ds_write_b32 v6, v2
	ds_read_b128 v[0:3], v8 offset:1536
	ds_read_b128 v[10:13], v8 offset:1792
	ds_read_b128 v[14:17], v8 offset:9728
	ds_read_b128 v[18:21], v8 offset:9984
	ds_read_b128 v[22:25], v8 offset:17920
	ds_read_b128 v[26:29], v8 offset:18176
	ds_read_b128 v[30:33], v8 offset:26112
	ds_read_b128 v[34:37], v8 offset:26368
	ds_read_b128 v[38:41], v8 offset:34304
	ds_read_b128 v[42:45], v8 offset:34560
	ds_read2_b32 v[86:87], v129 offset0:96 offset1:112
	ds_read_b64 v[88:89], v7 offset:43032
	v_pk_mul_f32 v[52:53], v[120:121], v[46:47]
	s_waitcnt lgkmcnt(15)
	v_pk_mul_f32 v[54:55], v[124:125], v[46:47]
	v_pk_fma_f32 v[48:49], v[58:59], v[50:51], v[48:49]
	v_pk_fma_f32 v[52:53], v[118:119], v[50:51], v[52:53]
	v_pk_mul_f32 v[56:57], v[102:103], v[50:51]
	v_pk_fma_f32 v[50:51], v[122:123], v[50:51], v[54:55]
	v_add_f32_e32 v48, v48, v49
	v_add_f32_e32 v49, v52, v53
	v_add_f32_e32 v50, v50, v51
	v_add_f32_dpp v48, v48, v48 quad_perm:[1,0,3,2] row_mask:0xf bank_mask:0xf bound_ctrl:1
	v_add_f32_dpp v49, v49, v49 quad_perm:[1,0,3,2] row_mask:0xf bank_mask:0xf bound_ctrl:1
	v_add_f32_dpp v50, v50, v50 quad_perm:[1,0,3,2] row_mask:0xf bank_mask:0xf bound_ctrl:1
	v_cndmask_b32_e32 v48, v48, v60, vcc
	v_add_f32_dpp v49, v49, v49 quad_perm:[2,3,0,1] row_mask:0xf bank_mask:0xf bound_ctrl:1
	v_add_f32_dpp v50, v50, v50 quad_perm:[2,3,0,1] row_mask:0xf bank_mask:0xf bound_ctrl:1
	v_add_f32_dpp v48, v48, v48 row_ror:2 row_mask:0xf bank_mask:0xf bound_ctrl:1
	v_add_f32_dpp v49, v49, v49 row_half_mirror row_mask:0xf bank_mask:0xf bound_ctrl:1
	v_pk_mul_f32 v[46:47], v[104:105], v[46:47]
	v_add_f32_dpp v50, v50, v50 row_half_mirror row_mask:0xf bank_mask:0xf bound_ctrl:1
	v_add_f32_dpp v48, v48, v48 row_ror:4 row_mask:0xf bank_mask:0xf bound_ctrl:1
	v_add_f32_dpp v151, v49, v49 row_mirror row_mask:0xf bank_mask:0xf bound_ctrl:1
	s_waitcnt lgkmcnt(14)
	v_mov_b32_e32 v150, v144
	v_pk_fma_f32 v[54:55], v[110:111], v[144:145], v[56:57] op_sel_hi:[1,0,1]
	v_pk_fma_f32 v[46:47], v[112:113], v[144:145], v[46:47] op_sel_hi:[1,0,1]
	v_add_f32_dpp v49, v50, v50 row_mirror row_mask:0xf bank_mask:0xf bound_ctrl:1
	v_add_f32_dpp v50, v48, v48 row_ror:8 row_mask:0xf bank_mask:0xf bound_ctrl:1
	s_waitcnt lgkmcnt(13)
	v_pk_mul_f32 v[92:93], v[150:151], v[146:147]
	v_pk_fma_f32 v[102:103], v[136:137], v[150:151], v[46:47] op_sel:[0,1,0]
	v_pk_fma_f32 v[104:105], v[134:135], v[150:151], v[54:55] op_sel:[0,1,0]
	v_mov_b32_e32 v152, v145
	v_add_f32_e32 v91, v92, v49
	v_pk_mul_f32 v[106:107], v[106:107], v[104:105]
	v_pk_mul_f32 v[108:109], v[108:109], v[102:103]
	v_sub_f32_e32 v92, v91, v93
	v_pk_mul_f32 v[96:97], v[96:97], v[102:103]
	v_pk_fma_f32 v[102:103], v[116:117], v[152:153], v[108:109] op_sel_hi:[1,0,1]
	v_pk_fma_f32 v[106:107], v[114:115], v[152:153], v[106:107] op_sel_hi:[1,0,1]
	v_pk_fma_f32 v[94:95], v[94:95], v[104:105], v[96:97]
	v_pk_fma_f32 v[96:97], v[138:139], v[92:93], v[106:107] op_sel_hi:[1,0,1]
	v_pk_fma_f32 v[92:93], v[140:141], v[92:93], v[102:103] op_sel_hi:[1,0,1]
	v_add_f32_e32 v91, v94, v95
	v_pk_mul_f32 v[94:95], v[100:101], v[92:93]
	s_waitcnt lgkmcnt(5)
	ds_write_b32 v6, v50 offset:128
	ds_read_b128 v[46:49], v8 offset:2048
	ds_read_b128 v[50:53], v8 offset:2304
	ds_read_b128 v[54:57], v8 offset:10240
	ds_read_b128 v[58:61], v8 offset:10496
	ds_read_b128 v[62:65], v8 offset:18432
	ds_read_b128 v[66:69], v8 offset:18688
	ds_read_b128 v[70:73], v8 offset:26624
	ds_read_b128 v[74:77], v8 offset:26880
	ds_read_b128 v[78:81], v8 offset:34816
	ds_read_b128 v[82:85], v8 offset:35072
	ds_read2_b32 v[112:113], v129 offset0:128 offset1:144
	ds_read_b64 v[118:119], v7 offset:43040
	v_pk_mul_f32 v[32:33], v[32:33], v[92:93]
	s_waitcnt lgkmcnt(15)
	v_pk_mul_f32 v[36:37], v[36:37], v[92:93]
	v_pk_mul_f32 v[16:17], v[16:17], v[92:93]
	v_pk_mul_f32 v[14:15], v[14:15], v[96:97]
	v_pk_fma_f32 v[92:93], v[98:99], v[96:97], v[94:95]
	v_pk_fma_f32 v[30:31], v[30:31], v[96:97], v[32:33]
	s_waitcnt lgkmcnt(14)
	v_pk_fma_f32 v[14:15], v[22:23], v[86:87], v[14:15] op_sel_hi:[1,0,1]
	v_add_f32_e32 v22, v92, v93
	v_add_f32_e32 v23, v30, v31
	v_add_f32_dpp v91, v91, v91 quad_perm:[1,0,3,2] row_mask:0xf bank_mask:0xf bound_ctrl:1
	v_pk_fma_f32 v[32:33], v[34:35], v[96:97], v[36:37]
	v_add_f32_dpp v22, v22, v22 quad_perm:[1,0,3,2] row_mask:0xf bank_mask:0xf bound_ctrl:1
	v_add_f32_dpp v23, v23, v23 quad_perm:[1,0,3,2] row_mask:0xf bank_mask:0xf bound_ctrl:1
	v_pk_fma_f32 v[16:17], v[24:25], v[86:87], v[16:17] op_sel_hi:[1,0,1]
	v_add_f32_e32 v24, v32, v33
	v_cndmask_b32_e32 v22, v22, v91, vcc
	v_add_f32_dpp v23, v23, v23 quad_perm:[2,3,0,1] row_mask:0xf bank_mask:0xf bound_ctrl:1
	v_add_f32_dpp v24, v24, v24 quad_perm:[1,0,3,2] row_mask:0xf bank_mask:0xf bound_ctrl:1
	v_add_f32_dpp v22, v22, v22 row_ror:2 row_mask:0xf bank_mask:0xf bound_ctrl:1
	v_add_f32_dpp v23, v23, v23 row_half_mirror row_mask:0xf bank_mask:0xf bound_ctrl:1
	v_add_f32_dpp v24, v24, v24 quad_perm:[2,3,0,1] row_mask:0xf bank_mask:0xf bound_ctrl:1
	v_add_f32_dpp v22, v22, v22 row_ror:4 row_mask:0xf bank_mask:0xf bound_ctrl:1
	v_add_f32_dpp v91, v23, v23 row_mirror row_mask:0xf bank_mask:0xf bound_ctrl:1
	v_mov_b32_e32 v90, v86
	v_add_f32_dpp v24, v24, v24 row_half_mirror row_mask:0xf bank_mask:0xf bound_ctrl:1
	v_add_f32_dpp v23, v22, v22 row_ror:8 row_mask:0xf bank_mask:0xf bound_ctrl:1
	v_add_f32_dpp v107, v24, v24 row_mirror row_mask:0xf bank_mask:0xf bound_ctrl:1
	s_waitcnt lgkmcnt(13)
; template <int CTRL> __device__ __forceinline__ float dppf(float x) { return __builtin_bit_cast(float, __builtin_amdgcn_mov_dpp(__builtin_bit_cast(int, x), CTRL, 0xf, 0xf, true)); }
; __device__ __forceinline__ float dot4(const f32x4& a, const f32x4& b) {
;     f32x2 t = __builtin_shufflevector(a, a, 0, 1) * __builtin_shufflevector(b, b, 0, 1);
;     t = __builtin_shufflevector(a, a, 2, 3) * __builtin_shufflevector(b, b, 2, 3) + t;
;     return t[0] + t[1];
; }
; __device__ __forceinline__ void reduce16x2(float& a, float& b) {
;     a += dppf<0xB1>(a); b += dppf<0xB1>(b); a += dppf<0x4E>(a); b += dppf<0x4E>(b);
;     a += dppf<0x141>(a); b += dppf<0x141>(b); a += dppf<0x140>(a); b += dppf<0x140>(b);
; }
; __device__ __forceinline__ void scan_unit(const Params& p, int unit) {
;     ...
;             for (int pr = 0; pr < SC_TC / 2; ++pr) {
;                 const int sn = 2 * pr + 2;
;                 const f32x4 r1n = SC_LD(0, sn), w1n = SC_LD(1, sn), k1n = SC_LD(2, sn), q1n = SC_LD(3, sn), n1n = SC_LD(4, sn);
;                 const f32x4 r2n = SC_LD(0, sn + 1), w2n = SC_LD(1, sn + 1), k2n = SC_LD(2, sn + 1), g2n = SC_LD(3, sn + 1), n2n = SC_LD(4, sn + 1);
;                 const float v1n = buf[SC_VOFF + sn * 16 + rl], v2n = buf[SC_VOFF + (sn + 1) * 16 + rl];
;                 const f32x2 cfn = *(const f32x2*)(buf + SC_COFF + (pr + 1) * 2);
;                 __builtin_amdgcn_sched_barrier(0x7);
;                 float d1 = dot4(S, q1), e2 = dot4(S, g2);
;                 const f32x4 t1 = S * w1 + v1 * k1;
;                 reduce16x2(d1, e2);
;                 const float d2 = e2 + v1 * cf[0] - d1 * cf[1];
;                 const f32x4 S1 = t1 + d1 * n1;
;                 const f32x4 S2 = (S1 * w2 + v2 * k2) + d2 * n2;
;                 float y1 = dot4(S1, r1), y2 = dot4(S2, r2);
;                 y1 += dppf<0xB1>(y1); y2 += dppf<0xB1>(y2);
;                 float yz = odd_lane ? y2 : y1;
;                 yz += dppf<0x122>(yz); yz += dppf<0x124>(yz); yz += dppf<0x128>(yz);
;                 yb[(2 * pr) * 16 + yoff] = yz;
;                 S = S2;
;                 r1 = r1n; w1 = w1n; k1 = k1n; q1 = q1n; n1 = n1n; r2 = r2n; w2 = w2n; k2 = k2n; g2 = g2n; n2 = n2n; v1 = v1n; v2 = v2n; cf = cfn;
	v_pk_mul_f32 v[120:121], v[90:91], v[88:89]
	v_pk_fma_f32 v[122:123], v[40:41], v[90:91], v[16:17] op_sel:[0,1,0]
	v_pk_fma_f32 v[124:125], v[38:39], v[90:91], v[14:15] op_sel:[0,1,0]
	v_add_f32_e32 v107, v120, v107
	v_pk_mul_f32 v[18:19], v[18:19], v[124:125]
	v_pk_mul_f32 v[20:21], v[20:21], v[122:123]
	v_pk_mul_f32 v[2:3], v[2:3], v[122:123]
	v_sub_f32_e32 v120, v107, v121
	v_pk_fma_f32 v[20:21], v[28:29], v[86:87], v[20:21] op_sel:[0,1,0]
	v_pk_fma_f32 v[18:19], v[26:27], v[86:87], v[18:19] op_sel:[0,1,0]
	v_pk_fma_f32 v[0:1], v[0:1], v[124:125], v[2:3]
	v_pk_fma_f32 v[2:3], v[42:43], v[120:121], v[18:19] op_sel_hi:[1,0,1]
	v_pk_fma_f32 v[18:19], v[44:45], v[120:121], v[20:21] op_sel_hi:[1,0,1]
	v_add_f32_e32 v20, v0, v1
	v_pk_mul_f32 v[0:1], v[12:13], v[18:19]
	s_waitcnt lgkmcnt(5)
	v_pk_mul_f32 v[12:13], v[72:73], v[18:19]
	v_add_f32_dpp v28, v20, v20 quad_perm:[1,0,3,2] row_mask:0xf bank_mask:0xf bound_ctrl:1
	s_waitcnt lgkmcnt(4)
	ds_write_b32 v6, v23 offset:256
	ds_read_b64 v[114:115], v7 offset:43048
	ds_read_b64 v[116:117], v7 offset:43056
	ds_read_b128 v[14:17], v8 offset:2560
	ds_read_b128 v[22:25], v8 offset:2816
	ds_read_b128 v[30:33], v8 offset:10752
	ds_read_b128 v[34:37], v8 offset:11008
	ds_read_b128 v[38:41], v8 offset:18944
	ds_read_b128 v[86:89], v8 offset:19200
	ds_read_b128 v[90:93], v8 offset:27136
	ds_read_b128 v[94:97], v8 offset:27392
	ds_read_b128 v[98:101], v8 offset:35328
	ds_read_b128 v[102:105], v8 offset:35584
	ds_read2_b32 v[126:127], v129 offset0:160 offset1:176
	v_pk_mul_f32 v[20:21], v[76:77], v[18:19]
	v_pk_fma_f32 v[0:1], v[10:11], v[2:3], v[0:1]
	v_pk_fma_f32 v[10:11], v[70:71], v[2:3], v[12:13]
	v_pk_mul_f32 v[26:27], v[54:55], v[2:3]
	v_pk_fma_f32 v[2:3], v[74:75], v[2:3], v[20:21]
	v_add_f32_e32 v0, v0, v1
	v_add_f32_e32 v1, v10, v11
	v_add_f32_e32 v2, v2, v3
	v_add_f32_dpp v0, v0, v0 quad_perm:[1,0,3,2] row_mask:0xf bank_mask:0xf bound_ctrl:1
	v_add_f32_dpp v1, v1, v1 quad_perm:[1,0,3,2] row_mask:0xf bank_mask:0xf bound_ctrl:1
	v_add_f32_dpp v2, v2, v2 quad_perm:[1,0,3,2] row_mask:0xf bank_mask:0xf bound_ctrl:1
	v_cndmask_b32_e32 v0, v0, v28, vcc
	v_add_f32_dpp v1, v1, v1 quad_perm:[2,3,0,1] row_mask:0xf bank_mask:0xf bound_ctrl:1
	v_add_f32_dpp v2, v2, v2 quad_perm:[2,3,0,1] row_mask:0xf bank_mask:0xf bound_ctrl:1
	v_add_f32_dpp v0, v0, v0 row_ror:2 row_mask:0xf bank_mask:0xf bound_ctrl:1
	v_add_f32_dpp v1, v1, v1 row_half_mirror row_mask:0xf bank_mask:0xf bound_ctrl:1
	v_pk_mul_f32 v[18:19], v[56:57], v[18:19]
	v_add_f32_dpp v2, v2, v2 row_half_mirror row_mask:0xf bank_mask:0xf bound_ctrl:1
	v_add_f32_dpp v0, v0, v0 row_ror:4 row_mask:0xf bank_mask:0xf bound_ctrl:1
	v_add_f32_dpp v107, v1, v1 row_mirror row_mask:0xf bank_mask:0xf bound_ctrl:1
	s_waitcnt lgkmcnt(15)
	v_mov_b32_e32 v106, v112
	v_pk_fma_f32 v[12:13], v[62:63], v[112:113], v[26:27] op_sel_hi:[1,0,1]
	v_pk_fma_f32 v[18:19], v[64:65], v[112:113], v[18:19] op_sel_hi:[1,0,1]
	v_add_f32_dpp v1, v2, v2 row_mirror row_mask:0xf bank_mask:0xf bound_ctrl:1
	v_add_f32_dpp v2, v0, v0 row_ror:8 row_mask:0xf bank_mask:0xf bound_ctrl:1
	v_mov_b32_e32 v0, v107
	s_waitcnt lgkmcnt(14)
	v_pk_mul_f32 v[118:119], v[106:107], v[118:119]
	v_pk_fma_f32 v[106:107], v[80:81], v[0:1], v[18:19] op_sel_hi:[1,0,1]
	v_pk_fma_f32 v[120:121], v[78:79], v[0:1], v[12:13] op_sel_hi:[1,0,1]
	v_add_f32_e32 v109, v118, v1
	v_pk_mul_f32 v[58:59], v[58:59], v[120:121]
	v_pk_mul_f32 v[60:61], v[60:61], v[106:107]
	v_sub_f32_e32 v118, v109, v119
	v_pk_mul_f32 v[48:49], v[48:49], v[106:107]
	v_pk_fma_f32 v[60:61], v[68:69], v[112:113], v[60:61] op_sel:[0,1,0]
	v_pk_fma_f32 v[58:59], v[66:67], v[112:113], v[58:59] op_sel:[0,1,0]
	v_pk_fma_f32 v[46:47], v[46:47], v[120:121], v[48:49]
	v_pk_fma_f32 v[48:49], v[82:83], v[118:119], v[58:59] op_sel_hi:[1,0,1]
	v_pk_fma_f32 v[58:59], v[84:85], v[118:119], v[60:61] op_sel_hi:[1,0,1]
	v_add_f32_e32 v60, v46, v47
	v_pk_mul_f32 v[46:47], v[52:53], v[58:59]
	s_waitcnt lgkmcnt(4)
	ds_write_b32 v6, v2 offset:384
	ds_read_b128 v[0:3], v8 offset:3072
	ds_read_b128 v[10:13], v8 offset:3328
	ds_read_b128 v[18:21], v8 offset:11264
	ds_read_b128 v[26:29], v8 offset:11520
	ds_read_b128 v[42:45], v8 offset:19456
	ds_read_b128 v[54:57], v8 offset:19712
	ds_read_b128 v[62:65], v8 offset:27648
	ds_read_b128 v[70:73], v8 offset:27904
	ds_read_b128 v[74:77], v8 offset:35840
	ds_read_b128 v[78:81], v8 offset:36096
	ds_read2_b32 v[122:123], v129 offset0:192 offset1:208
	v_pk_mul_f32 v[52:53], v[92:93], v[58:59]
	v_add_f32_dpp v66, v60, v60 quad_perm:[1,0,3,2] row_mask:0xf bank_mask:0xf bound_ctrl:1
	s_waitcnt lgkmcnt(15)
	v_pk_mul_f32 v[60:61], v[96:97], v[58:59]
	v_pk_mul_f32 v[30:31], v[30:31], v[48:49]
	v_pk_fma_f32 v[46:47], v[50:51], v[48:49], v[46:47]
	v_pk_fma_f32 v[50:51], v[90:91], v[48:49], v[52:53]
	v_pk_mul_f32 v[32:33], v[32:33], v[58:59]
	v_pk_fma_f32 v[48:49], v[94:95], v[48:49], v[60:61]
	s_waitcnt lgkmcnt(12)
; template <int CTRL> __device__ __forceinline__ float dppf(float x) { return __builtin_bit_cast(float, __builtin_amdgcn_mov_dpp(__builtin_bit_cast(int, x), CTRL, 0xf, 0xf, true)); }
; __device__ __forceinline__ float dot4(const f32x4& a, const f32x4& b) {
;     f32x2 t = __builtin_shufflevector(a, a, 0, 1) * __builtin_shufflevector(b, b, 0, 1);
;     t = __builtin_shufflevector(a, a, 2, 3) * __builtin_shufflevector(b, b, 2, 3) + t;
;     return t[0] + t[1];
; }
; __device__ __forceinline__ void reduce16x2(float& a, float& b) {
;     a += dppf<0xB1>(a); b += dppf<0xB1>(b); a += dppf<0x4E>(a); b += dppf<0x4E>(b);
;     a += dppf<0x141>(a); b += dppf<0x141>(b); a += dppf<0x140>(a); b += dppf<0x140>(b);
; }
; __device__ __forceinline__ void scan_unit(const Params& p, int unit) {
;     ...
;             for (int pr = 0; pr < SC_TC / 2; ++pr) {
;                 const int sn = 2 * pr + 2;
;                 const f32x4 r1n = SC_LD(0, sn), w1n = SC_LD(1, sn), k1n = SC_LD(2, sn), q1n = SC_LD(3, sn), n1n = SC_LD(4, sn);
;                 const f32x4 r2n = SC_LD(0, sn + 1), w2n = SC_LD(1, sn + 1), k2n = SC_LD(2, sn + 1), g2n = SC_LD(3, sn + 1), n2n = SC_LD(4, sn + 1);
;                 const float v1n = buf[SC_VOFF + sn * 16 + rl], v2n = buf[SC_VOFF + (sn + 1) * 16 + rl];
;                 const f32x2 cfn = *(const f32x2*)(buf + SC_COFF + (pr + 1) * 2);
;                 __builtin_amdgcn_sched_barrier(0x7);
;                 float d1 = dot4(S, q1), e2 = dot4(S, g2);
;                 const f32x4 t1 = S * w1 + v1 * k1;
;                 reduce16x2(d1, e2);
;                 const float d2 = e2 + v1 * cf[0] - d1 * cf[1];
;                 const f32x4 S1 = t1 + d1 * n1;
;                 const f32x4 S2 = (S1 * w2 + v2 * k2) + d2 * n2;
;                 float y1 = dot4(S1, r1), y2 = dot4(S2, r2);
;                 y1 += dppf<0xB1>(y1); y2 += dppf<0xB1>(y2);
;                 float yz = odd_lane ? y2 : y1;
;                 yz += dppf<0x122>(yz); yz += dppf<0x124>(yz); yz += dppf<0x128>(yz);
;                 yb[(2 * pr) * 16 + yoff] = yz;
;                 S = S2;
;                 r1 = r1n; w1 = w1n; k1 = k1n; q1 = q1n; n1 = n1n; r2 = r2n; w2 = w2n; k2 = k2n; g2 = g2n; n2 = n2n; v1 = v1n; v2 = v2n; cf = cfn;
	v_pk_fma_f32 v[30:31], v[38:39], v[126:127], v[30:31] op_sel_hi:[1,0,1]
	v_add_f32_e32 v38, v46, v47
	v_add_f32_e32 v39, v50, v51
	v_pk_fma_f32 v[32:33], v[40:41], v[126:127], v[32:33] op_sel_hi:[1,0,1]
	v_add_f32_e32 v40, v48, v49
	v_add_f32_dpp v38, v38, v38 quad_perm:[1,0,3,2] row_mask:0xf bank_mask:0xf bound_ctrl:1
	v_add_f32_dpp v39, v39, v39 quad_perm:[1,0,3,2] row_mask:0xf bank_mask:0xf bound_ctrl:1
	v_add_f32_dpp v40, v40, v40 quad_perm:[1,0,3,2] row_mask:0xf bank_mask:0xf bound_ctrl:1
	v_cndmask_b32_e32 v38, v38, v66, vcc
	v_add_f32_dpp v39, v39, v39 quad_perm:[2,3,0,1] row_mask:0xf bank_mask:0xf bound_ctrl:1
	v_add_f32_dpp v40, v40, v40 quad_perm:[2,3,0,1] row_mask:0xf bank_mask:0xf bound_ctrl:1
	v_add_f32_dpp v38, v38, v38 row_ror:2 row_mask:0xf bank_mask:0xf bound_ctrl:1
	v_add_f32_dpp v39, v39, v39 row_half_mirror row_mask:0xf bank_mask:0xf bound_ctrl:1
	v_add_f32_dpp v40, v40, v40 row_half_mirror row_mask:0xf bank_mask:0xf bound_ctrl:1
	v_add_f32_dpp v38, v38, v38 row_ror:4 row_mask:0xf bank_mask:0xf bound_ctrl:1
	v_add_f32_dpp v111, v39, v39 row_mirror row_mask:0xf bank_mask:0xf bound_ctrl:1
	v_mov_b32_e32 v110, v126
	v_add_f32_dpp v39, v40, v40 row_mirror row_mask:0xf bank_mask:0xf bound_ctrl:1
	v_add_f32_dpp v40, v38, v38 row_ror:8 row_mask:0xf bank_mask:0xf bound_ctrl:1
	v_mov_b32_e32 v38, v111
	v_pk_mul_f32 v[114:115], v[110:111], v[114:115]
	v_pk_fma_f32 v[110:111], v[100:101], v[38:39], v[32:33] op_sel_hi:[1,0,1]
	v_pk_fma_f32 v[118:119], v[98:99], v[38:39], v[30:31] op_sel_hi:[1,0,1]
	v_add_f32_e32 v107, v114, v39
	v_pk_mul_f32 v[34:35], v[34:35], v[118:119]
	v_pk_mul_f32 v[36:37], v[36:37], v[110:111]
	v_sub_f32_e32 v114, v107, v115
	v_pk_mul_f32 v[16:17], v[16:17], v[110:111]
	v_pk_fma_f32 v[36:37], v[88:89], v[126:127], v[36:37] op_sel:[0,1,0]
	v_pk_fma_f32 v[34:35], v[86:87], v[126:127], v[34:35] op_sel:[0,1,0]
	v_pk_fma_f32 v[14:15], v[14:15], v[118:119], v[16:17]
	v_pk_fma_f32 v[16:17], v[102:103], v[114:115], v[34:35] op_sel_hi:[1,0,1]
	v_pk_fma_f32 v[34:35], v[104:105], v[114:115], v[36:37] op_sel_hi:[1,0,1]
	v_add_f32_e32 v36, v14, v15
	v_pk_mul_f32 v[14:15], v[24:25], v[34:35]
	s_waitcnt lgkmcnt(4)
	ds_write_b32 v6, v40 offset:512
	ds_read_b128 v[30:33], v8 offset:3584
	ds_read_b128 v[38:41], v8 offset:3840
	ds_read_b128 v[46:49], v8 offset:11776
	ds_read_b128 v[50:53], v8 offset:12032
	ds_read_b128 v[58:61], v8 offset:19968
	ds_read_b128 v[66:69], v8 offset:20224
	ds_read_b128 v[82:85], v8 offset:28160
	ds_read_b128 v[90:93], v8 offset:28416
	ds_read_b128 v[94:97], v8 offset:36352
	ds_read_b128 v[98:101], v8 offset:36608
	ds_read2_b32 v[120:121], v129 offset0:224 offset1:240
	ds_read_b64 v[124:125], v7 offset:43064
	v_pk_mul_f32 v[24:25], v[64:65], v[34:35]
	v_add_f32_dpp v86, v36, v36 quad_perm:[1,0,3,2] row_mask:0xf bank_mask:0xf bound_ctrl:1
	s_waitcnt lgkmcnt(15)
	v_pk_mul_f32 v[36:37], v[72:73], v[34:35]
	v_pk_fma_f32 v[14:15], v[22:23], v[16:17], v[14:15]
	v_pk_fma_f32 v[22:23], v[62:63], v[16:17], v[24:25]
	v_pk_mul_f32 v[18:19], v[18:19], v[16:17]
	v_pk_fma_f32 v[16:17], v[70:71], v[16:17], v[36:37]
	v_add_f32_e32 v14, v14, v15
	v_add_f32_e32 v15, v22, v23
	v_add_f32_e32 v16, v16, v17
	v_add_f32_dpp v14, v14, v14 quad_perm:[1,0,3,2] row_mask:0xf bank_mask:0xf bound_ctrl:1
	v_add_f32_dpp v15, v15, v15 quad_perm:[1,0,3,2] row_mask:0xf bank_mask:0xf bound_ctrl:1
	v_add_f32_dpp v16, v16, v16 quad_perm:[1,0,3,2] row_mask:0xf bank_mask:0xf bound_ctrl:1
	v_cndmask_b32_e32 v14, v14, v86, vcc
	v_add_f32_dpp v15, v15, v15 quad_perm:[2,3,0,1] row_mask:0xf bank_mask:0xf bound_ctrl:1
	v_add_f32_dpp v16, v16, v16 quad_perm:[2,3,0,1] row_mask:0xf bank_mask:0xf bound_ctrl:1
	v_add_f32_dpp v14, v14, v14 row_ror:2 row_mask:0xf bank_mask:0xf bound_ctrl:1
	v_add_f32_dpp v15, v15, v15 row_half_mirror row_mask:0xf bank_mask:0xf bound_ctrl:1
	v_pk_mul_f32 v[20:21], v[20:21], v[34:35]
	v_add_f32_dpp v16, v16, v16 row_half_mirror row_mask:0xf bank_mask:0xf bound_ctrl:1
	v_add_f32_dpp v14, v14, v14 row_ror:4 row_mask:0xf bank_mask:0xf bound_ctrl:1
	v_add_f32_dpp v107, v15, v15 row_mirror row_mask:0xf bank_mask:0xf bound_ctrl:1
	s_waitcnt lgkmcnt(13)
	v_mov_b32_e32 v106, v122
	v_pk_fma_f32 v[18:19], v[42:43], v[122:123], v[18:19] op_sel_hi:[1,0,1]
	v_pk_fma_f32 v[20:21], v[44:45], v[122:123], v[20:21] op_sel_hi:[1,0,1]
	v_add_f32_dpp v15, v16, v16 row_mirror row_mask:0xf bank_mask:0xf bound_ctrl:1
	v_add_f32_dpp v16, v14, v14 row_ror:8 row_mask:0xf bank_mask:0xf bound_ctrl:1
	v_mov_b32_e32 v14, v107
	v_pk_mul_f32 v[114:115], v[106:107], v[116:117]
	v_pk_fma_f32 v[106:107], v[76:77], v[14:15], v[20:21] op_sel_hi:[1,0,1]
	v_pk_fma_f32 v[116:117], v[74:75], v[14:15], v[18:19] op_sel_hi:[1,0,1]
	v_add_f32_e32 v109, v114, v15
	v_pk_mul_f32 v[26:27], v[26:27], v[116:117]
	v_pk_mul_f32 v[28:29], v[28:29], v[106:107]
	v_sub_f32_e32 v114, v109, v115
	v_pk_mul_f32 v[2:3], v[2:3], v[106:107]
	v_pk_fma_f32 v[28:29], v[56:57], v[122:123], v[28:29] op_sel:[0,1,0]
	v_pk_fma_f32 v[26:27], v[54:55], v[122:123], v[26:27] op_sel:[0,1,0]
	v_pk_fma_f32 v[0:1], v[0:1], v[116:117], v[2:3]
	v_pk_fma_f32 v[2:3], v[78:79], v[114:115], v[26:27] op_sel_hi:[1,0,1]
	v_pk_fma_f32 v[26:27], v[80:81], v[114:115], v[28:29] op_sel_hi:[1,0,1]
	v_add_f32_e32 v28, v0, v1
	v_pk_mul_f32 v[0:1], v[12:13], v[26:27]
	s_waitcnt lgkmcnt(5)
; template <int CTRL> __device__ __forceinline__ float dppf(float x) { return __builtin_bit_cast(float, __builtin_amdgcn_mov_dpp(__builtin_bit_cast(int, x), CTRL, 0xf, 0xf, true)); }
; __device__ __forceinline__ float dot4(const f32x4& a, const f32x4& b) {
;     f32x2 t = __builtin_shufflevector(a, a, 0, 1) * __builtin_shufflevector(b, b, 0, 1);
;     t = __builtin_shufflevector(a, a, 2, 3) * __builtin_shufflevector(b, b, 2, 3) + t;
;     return t[0] + t[1];
; }
; __device__ __forceinline__ void reduce16x2(float& a, float& b) {
;     a += dppf<0xB1>(a); b += dppf<0xB1>(b); a += dppf<0x4E>(a); b += dppf<0x4E>(b);
;     a += dppf<0x141>(a); b += dppf<0x141>(b); a += dppf<0x140>(a); b += dppf<0x140>(b);
; }
; __device__ __forceinline__ void scan_unit(const Params& p, int unit) {
;     ...
;             for (int pr = 0; pr < SC_TC / 2; ++pr) {
;                 const int sn = 2 * pr + 2;
;                 const f32x4 r1n = SC_LD(0, sn), w1n = SC_LD(1, sn), k1n = SC_LD(2, sn), q1n = SC_LD(3, sn), n1n = SC_LD(4, sn);
;                 const f32x4 r2n = SC_LD(0, sn + 1), w2n = SC_LD(1, sn + 1), k2n = SC_LD(2, sn + 1), g2n = SC_LD(3, sn + 1), n2n = SC_LD(4, sn + 1);
;                 const float v1n = buf[SC_VOFF + sn * 16 + rl], v2n = buf[SC_VOFF + (sn + 1) * 16 + rl];
;                 const f32x2 cfn = *(const f32x2*)(buf + SC_COFF + (pr + 1) * 2);
;                 __builtin_amdgcn_sched_barrier(0x7);
;                 float d1 = dot4(S, q1), e2 = dot4(S, g2);
;                 const f32x4 t1 = S * w1 + v1 * k1;
;                 reduce16x2(d1, e2);
;                 const float d2 = e2 + v1 * cf[0] - d1 * cf[1];
;                 const f32x4 S1 = t1 + d1 * n1;
;                 const f32x4 S2 = (S1 * w2 + v2 * k2) + d2 * n2;
;                 float y1 = dot4(S1, r1), y2 = dot4(S2, r2);
;                 y1 += dppf<0xB1>(y1); y2 += dppf<0xB1>(y2);
;                 float yz = odd_lane ? y2 : y1;
;                 yz += dppf<0x122>(yz); yz += dppf<0x124>(yz); yz += dppf<0x128>(yz);
;                 yb[(2 * pr) * 16 + yoff] = yz;
;                 S = S2;
;                 r1 = r1n; w1 = w1n; k1 = k1n; q1 = q1n; n1 = n1n; r2 = r2n; w2 = w2n; k2 = k2n; g2 = g2n; n2 = n2n; v1 = v1n; v2 = v2n; cf = cfn;
	ds_write_b32 v6, v16 offset:640
	v_add_u32_e32 v9, 0xa400, v9
	ds_read_b128 v[14:17], v8 offset:4096
	ds_read_b128 v[18:21], v8 offset:4352
	ds_read_b128 v[22:25], v8 offset:12288
	ds_read_b128 v[34:37], v8 offset:12544
	ds_read_b128 v[42:45], v8 offset:20480
	ds_read_b128 v[62:65], v8 offset:20736
	ds_read_b128 v[70:73], v8 offset:28672
	ds_read_b128 v[74:77], v8 offset:28928
	ds_read_b128 v[86:89], v8 offset:36864
	ds_read_b128 v[102:105], v8 offset:37120
	ds_read2_b32 v[118:119], v9 offset1:16
	ds_read_b64 v[122:123], v7 offset:43072
	v_pk_mul_f32 v[12:13], v[84:85], v[26:27]
	v_pk_fma_f32 v[0:1], v[10:11], v[2:3], v[0:1]
	v_pk_fma_f32 v[10:11], v[82:83], v[2:3], v[12:13]
	v_add_f32_dpp v54, v28, v28 quad_perm:[1,0,3,2] row_mask:0xf bank_mask:0xf bound_ctrl:1
	s_waitcnt lgkmcnt(15)
	v_pk_mul_f32 v[28:29], v[92:93], v[26:27]
	v_add_f32_e32 v0, v0, v1
	v_add_f32_e32 v1, v10, v11
	v_pk_mul_f32 v[46:47], v[46:47], v[2:3]
	v_pk_fma_f32 v[2:3], v[90:91], v[2:3], v[28:29]
	v_add_f32_dpp v0, v0, v0 quad_perm:[1,0,3,2] row_mask:0xf bank_mask:0xf bound_ctrl:1
	v_add_f32_dpp v1, v1, v1 quad_perm:[1,0,3,2] row_mask:0xf bank_mask:0xf bound_ctrl:1
	v_add_f32_e32 v2, v2, v3
	v_cndmask_b32_e32 v0, v0, v54, vcc
	v_add_f32_dpp v1, v1, v1 quad_perm:[2,3,0,1] row_mask:0xf bank_mask:0xf bound_ctrl:1
	v_add_f32_dpp v2, v2, v2 quad_perm:[1,0,3,2] row_mask:0xf bank_mask:0xf bound_ctrl:1
	v_add_f32_dpp v0, v0, v0 row_ror:2 row_mask:0xf bank_mask:0xf bound_ctrl:1
	v_add_f32_dpp v1, v1, v1 row_half_mirror row_mask:0xf bank_mask:0xf bound_ctrl:1
	v_pk_mul_f32 v[26:27], v[48:49], v[26:27]
	v_add_f32_dpp v2, v2, v2 quad_perm:[2,3,0,1] row_mask:0xf bank_mask:0xf bound_ctrl:1
	v_add_f32_dpp v0, v0, v0 row_ror:4 row_mask:0xf bank_mask:0xf bound_ctrl:1
	v_add_f32_dpp v111, v1, v1 row_mirror row_mask:0xf bank_mask:0xf bound_ctrl:1
	s_waitcnt lgkmcnt(14)
	v_mov_b32_e32 v110, v120
	v_pk_fma_f32 v[12:13], v[58:59], v[120:121], v[46:47] op_sel_hi:[1,0,1]
	v_pk_fma_f32 v[26:27], v[60:61], v[120:121], v[26:27] op_sel_hi:[1,0,1]
	v_add_f32_dpp v2, v2, v2 row_half_mirror row_mask:0xf bank_mask:0xf bound_ctrl:1
	v_add_f32_dpp v1, v0, v0 row_ror:8 row_mask:0xf bank_mask:0xf bound_ctrl:1
	v_mov_b32_e32 v0, v111
	v_mov_b32_e32 v112, v121
	v_add_f32_dpp v107, v2, v2 row_mirror row_mask:0xf bank_mask:0xf bound_ctrl:1
	s_waitcnt lgkmcnt(13)
	v_pk_mul_f32 v[110:111], v[110:111], v[124:125]
	v_pk_fma_f32 v[120:121], v[96:97], v[0:1], v[26:27] op_sel_hi:[1,0,1]
	v_pk_fma_f32 v[124:125], v[94:95], v[0:1], v[12:13] op_sel_hi:[1,0,1]
	v_add_f32_e32 v107, v110, v107
	v_pk_mul_f32 v[50:51], v[50:51], v[124:125]
	v_pk_mul_f32 v[52:53], v[52:53], v[120:121]
	v_pk_mul_f32 v[32:33], v[32:33], v[120:121]
	v_sub_f32_e32 v110, v107, v111
	v_pk_fma_f32 v[52:53], v[68:69], v[112:113], v[52:53] op_sel_hi:[1,0,1]
	v_pk_fma_f32 v[50:51], v[66:67], v[112:113], v[50:51] op_sel_hi:[1,0,1]
	v_pk_fma_f32 v[30:31], v[30:31], v[124:125], v[32:33]
	v_pk_fma_f32 v[32:33], v[98:99], v[110:111], v[50:51] op_sel_hi:[1,0,1]
	v_pk_fma_f32 v[50:51], v[100:101], v[110:111], v[52:53] op_sel_hi:[1,0,1]
	v_add_f32_e32 v52, v30, v31
	v_pk_mul_f32 v[30:31], v[40:41], v[50:51]
	s_waitcnt lgkmcnt(5)
	v_pk_mul_f32 v[40:41], v[72:73], v[50:51]
	v_add_f32_dpp v66, v52, v52 quad_perm:[1,0,3,2] row_mask:0xf bank_mask:0xf bound_ctrl:1
	s_waitcnt lgkmcnt(4)
	ds_write_b32 v6, v1 offset:768
	ds_read_b64 v[114:115], v7 offset:43080
	ds_read_b64 v[116:117], v7 offset:43088
	ds_read_b128 v[0:3], v8 offset:4608
	ds_read_b128 v[10:13], v8 offset:4864
	ds_read_b128 v[26:29], v8 offset:12800
	ds_read_b128 v[46:49], v8 offset:13056
	ds_read_b128 v[54:57], v8 offset:20992
	ds_read_b128 v[58:61], v8 offset:21248
	ds_read_b128 v[78:81], v8 offset:29184
	ds_read_b128 v[82:85], v8 offset:29440
	ds_read_b128 v[90:93], v8 offset:37376
	ds_read_b128 v[94:97], v8 offset:37632
	ds_read2_b32 v[126:127], v9 offset0:32 offset1:48
	v_pk_mul_f32 v[52:53], v[76:77], v[50:51]
	v_pk_fma_f32 v[30:31], v[38:39], v[32:33], v[30:31]
	v_pk_fma_f32 v[38:39], v[70:71], v[32:33], v[40:41]
	v_pk_mul_f32 v[22:23], v[22:23], v[32:33]
	v_pk_fma_f32 v[32:33], v[74:75], v[32:33], v[52:53]
	v_add_f32_e32 v30, v30, v31
	v_add_f32_e32 v31, v38, v39
	v_add_f32_e32 v32, v32, v33
	v_add_f32_dpp v30, v30, v30 quad_perm:[1,0,3,2] row_mask:0xf bank_mask:0xf bound_ctrl:1
	v_add_f32_dpp v31, v31, v31 quad_perm:[1,0,3,2] row_mask:0xf bank_mask:0xf bound_ctrl:1
	v_add_f32_dpp v32, v32, v32 quad_perm:[1,0,3,2] row_mask:0xf bank_mask:0xf bound_ctrl:1
	v_cndmask_b32_e32 v30, v30, v66, vcc
	v_add_f32_dpp v31, v31, v31 quad_perm:[2,3,0,1] row_mask:0xf bank_mask:0xf bound_ctrl:1
	v_add_f32_dpp v32, v32, v32 quad_perm:[2,3,0,1] row_mask:0xf bank_mask:0xf bound_ctrl:1
	v_add_f32_dpp v30, v30, v30 row_ror:2 row_mask:0xf bank_mask:0xf bound_ctrl:1
	v_add_f32_dpp v31, v31, v31 row_half_mirror row_mask:0xf bank_mask:0xf bound_ctrl:1
	v_pk_mul_f32 v[24:25], v[24:25], v[50:51]
	v_add_f32_dpp v32, v32, v32 row_half_mirror row_mask:0xf bank_mask:0xf bound_ctrl:1
	v_add_f32_dpp v30, v30, v30 row_ror:4 row_mask:0xf bank_mask:0xf bound_ctrl:1
	v_add_f32_dpp v107, v31, v31 row_mirror row_mask:0xf bank_mask:0xf bound_ctrl:1
	s_waitcnt lgkmcnt(15)
	v_mov_b32_e32 v106, v118
	v_pk_fma_f32 v[22:23], v[42:43], v[118:119], v[22:23] op_sel_hi:[1,0,1]
	v_pk_fma_f32 v[24:25], v[44:45], v[118:119], v[24:25] op_sel_hi:[1,0,1]
	v_add_f32_dpp v31, v32, v32 row_mirror row_mask:0xf bank_mask:0xf bound_ctrl:1
	v_add_f32_dpp v32, v30, v30 row_ror:8 row_mask:0xf bank_mask:0xf bound_ctrl:1
	v_mov_b32_e32 v30, v107
	v_mov_b32_e32 v108, v119
	s_waitcnt lgkmcnt(14)
; template <int CTRL> __device__ __forceinline__ float dppf(float x) { return __builtin_bit_cast(float, __builtin_amdgcn_mov_dpp(__builtin_bit_cast(int, x), CTRL, 0xf, 0xf, true)); }
; __device__ __forceinline__ float dot4(const f32x4& a, const f32x4& b) {
;     f32x2 t = __builtin_shufflevector(a, a, 0, 1) * __builtin_shufflevector(b, b, 0, 1);
;     t = __builtin_shufflevector(a, a, 2, 3) * __builtin_shufflevector(b, b, 2, 3) + t;
;     return t[0] + t[1];
; }
; __device__ __forceinline__ void reduce16x2(float& a, float& b) {
;     a += dppf<0xB1>(a); b += dppf<0xB1>(b); a += dppf<0x4E>(a); b += dppf<0x4E>(b);
;     a += dppf<0x141>(a); b += dppf<0x141>(b); a += dppf<0x140>(a); b += dppf<0x140>(b);
; }
; __device__ __forceinline__ void scan_unit(const Params& p, int unit) {
;     ...
;             for (int pr = 0; pr < SC_TC / 2; ++pr) {
;                 const int sn = 2 * pr + 2;
;                 const f32x4 r1n = SC_LD(0, sn), w1n = SC_LD(1, sn), k1n = SC_LD(2, sn), q1n = SC_LD(3, sn), n1n = SC_LD(4, sn);
;                 const f32x4 r2n = SC_LD(0, sn + 1), w2n = SC_LD(1, sn + 1), k2n = SC_LD(2, sn + 1), g2n = SC_LD(3, sn + 1), n2n = SC_LD(4, sn + 1);
;                 const float v1n = buf[SC_VOFF + sn * 16 + rl], v2n = buf[SC_VOFF + (sn + 1) * 16 + rl];
;                 const f32x2 cfn = *(const f32x2*)(buf + SC_COFF + (pr + 1) * 2);
;                 __builtin_amdgcn_sched_barrier(0x7);
;                 float d1 = dot4(S, q1), e2 = dot4(S, g2);
;                 const f32x4 t1 = S * w1 + v1 * k1;
;                 reduce16x2(d1, e2);
;                 const float d2 = e2 + v1 * cf[0] - d1 * cf[1];
;                 const f32x4 S1 = t1 + d1 * n1;
;                 const f32x4 S2 = (S1 * w2 + v2 * k2) + d2 * n2;
;                 float y1 = dot4(S1, r1), y2 = dot4(S2, r2);
;                 y1 += dppf<0xB1>(y1); y2 += dppf<0xB1>(y2);
;                 float yz = odd_lane ? y2 : y1;
;                 yz += dppf<0x122>(yz); yz += dppf<0x124>(yz); yz += dppf<0x128>(yz);
;                 yb[(2 * pr) * 16 + yoff] = yz;
;                 S = S2;
;                 r1 = r1n; w1 = w1n; k1 = k1n; q1 = q1n; n1 = n1n; r2 = r2n; w2 = w2n; k2 = k2n; g2 = g2n; n2 = n2n; v1 = v1n; v2 = v2n; cf = cfn;
	v_pk_mul_f32 v[118:119], v[106:107], v[122:123]
	v_pk_fma_f32 v[106:107], v[88:89], v[30:31], v[24:25] op_sel_hi:[1,0,1]
	v_pk_fma_f32 v[120:121], v[86:87], v[30:31], v[22:23] op_sel_hi:[1,0,1]
	v_add_f32_e32 v109, v118, v31
	v_pk_mul_f32 v[34:35], v[34:35], v[120:121]
	v_pk_mul_f32 v[36:37], v[36:37], v[106:107]
	v_sub_f32_e32 v118, v109, v119
	v_pk_mul_f32 v[16:17], v[16:17], v[106:107]
	v_pk_fma_f32 v[36:37], v[64:65], v[108:109], v[36:37] op_sel_hi:[1,0,1]
	v_pk_fma_f32 v[34:35], v[62:63], v[108:109], v[34:35] op_sel_hi:[1,0,1]
	v_pk_fma_f32 v[14:15], v[14:15], v[120:121], v[16:17]
	v_pk_fma_f32 v[16:17], v[102:103], v[118:119], v[34:35] op_sel_hi:[1,0,1]
	v_pk_fma_f32 v[34:35], v[104:105], v[118:119], v[36:37] op_sel_hi:[1,0,1]
	v_add_f32_e32 v36, v14, v15
	v_pk_mul_f32 v[14:15], v[20:21], v[34:35]
	s_waitcnt lgkmcnt(4)
	ds_write_b32 v6, v32 offset:896
	ds_read_b128 v[22:25], v8 offset:5120
	ds_read_b128 v[30:33], v8 offset:5376
	ds_read_b128 v[38:41], v8 offset:13312
	ds_read_b128 v[42:45], v8 offset:13568
	ds_read_b128 v[50:53], v8 offset:21504
	ds_read_b128 v[66:69], v8 offset:21760
	ds_read_b128 v[70:73], v8 offset:29696
	ds_read_b128 v[74:77], v8 offset:29952
	ds_read_b128 v[86:89], v8 offset:37888
	ds_read_b128 v[98:101], v8 offset:38144
	ds_read2_b32 v[122:123], v9 offset0:64 offset1:80
	v_pk_mul_f32 v[20:21], v[80:81], v[34:35]
	v_add_f32_dpp v62, v36, v36 quad_perm:[1,0,3,2] row_mask:0xf bank_mask:0xf bound_ctrl:1
	s_waitcnt lgkmcnt(15)
	v_pk_mul_f32 v[36:37], v[84:85], v[34:35]
	v_pk_fma_f32 v[14:15], v[18:19], v[16:17], v[14:15]
	v_pk_fma_f32 v[18:19], v[78:79], v[16:17], v[20:21]
	v_pk_mul_f32 v[26:27], v[26:27], v[16:17]
	v_pk_fma_f32 v[16:17], v[82:83], v[16:17], v[36:37]
	v_add_f32_e32 v14, v14, v15
	v_add_f32_e32 v15, v18, v19
	v_add_f32_e32 v16, v16, v17
	v_add_f32_dpp v14, v14, v14 quad_perm:[1,0,3,2] row_mask:0xf bank_mask:0xf bound_ctrl:1
	v_add_f32_dpp v15, v15, v15 quad_perm:[1,0,3,2] row_mask:0xf bank_mask:0xf bound_ctrl:1
	v_add_f32_dpp v16, v16, v16 quad_perm:[1,0,3,2] row_mask:0xf bank_mask:0xf bound_ctrl:1
	v_cndmask_b32_e32 v14, v14, v62, vcc
	v_add_f32_dpp v15, v15, v15 quad_perm:[2,3,0,1] row_mask:0xf bank_mask:0xf bound_ctrl:1
	v_add_f32_dpp v16, v16, v16 quad_perm:[2,3,0,1] row_mask:0xf bank_mask:0xf bound_ctrl:1
	v_add_f32_dpp v14, v14, v14 row_ror:2 row_mask:0xf bank_mask:0xf bound_ctrl:1
	v_add_f32_dpp v15, v15, v15 row_half_mirror row_mask:0xf bank_mask:0xf bound_ctrl:1
	v_pk_mul_f32 v[28:29], v[28:29], v[34:35]
	v_add_f32_dpp v16, v16, v16 row_half_mirror row_mask:0xf bank_mask:0xf bound_ctrl:1
	v_add_f32_dpp v14, v14, v14 row_ror:4 row_mask:0xf bank_mask:0xf bound_ctrl:1
	v_add_f32_dpp v111, v15, v15 row_mirror row_mask:0xf bank_mask:0xf bound_ctrl:1
	s_waitcnt lgkmcnt(12)
	v_mov_b32_e32 v110, v126
	v_pk_fma_f32 v[20:21], v[54:55], v[126:127], v[26:27] op_sel_hi:[1,0,1]
	v_pk_fma_f32 v[26:27], v[56:57], v[126:127], v[28:29] op_sel_hi:[1,0,1]
	v_add_f32_dpp v15, v16, v16 row_mirror row_mask:0xf bank_mask:0xf bound_ctrl:1
	v_add_f32_dpp v16, v14, v14 row_ror:8 row_mask:0xf bank_mask:0xf bound_ctrl:1
	v_mov_b32_e32 v14, v111
	v_pk_mul_f32 v[114:115], v[110:111], v[114:115]
	v_pk_fma_f32 v[110:111], v[92:93], v[14:15], v[26:27] op_sel_hi:[1,0,1]
	v_pk_fma_f32 v[118:119], v[90:91], v[14:15], v[20:21] op_sel_hi:[1,0,1]
	v_add_f32_e32 v107, v114, v15
	v_pk_mul_f32 v[46:47], v[46:47], v[118:119]
	v_pk_mul_f32 v[48:49], v[48:49], v[110:111]
	v_sub_f32_e32 v114, v107, v115
	v_pk_mul_f32 v[2:3], v[2:3], v[110:111]
	v_pk_fma_f32 v[48:49], v[60:61], v[126:127], v[48:49] op_sel:[0,1,0]
	v_pk_fma_f32 v[46:47], v[58:59], v[126:127], v[46:47] op_sel:[0,1,0]
	v_pk_fma_f32 v[0:1], v[0:1], v[118:119], v[2:3]
	v_pk_fma_f32 v[2:3], v[94:95], v[114:115], v[46:47] op_sel_hi:[1,0,1]
	v_pk_fma_f32 v[46:47], v[96:97], v[114:115], v[48:49] op_sel_hi:[1,0,1]
	v_add_f32_e32 v48, v0, v1
	v_pk_mul_f32 v[0:1], v[12:13], v[46:47]
	s_waitcnt lgkmcnt(4)
	ds_write_b32 v6, v16 offset:1024
	ds_read_b128 v[14:17], v8 offset:5632
	ds_read_b128 v[18:21], v8 offset:5888
	ds_read_b128 v[26:29], v8 offset:13824
	ds_read_b128 v[34:37], v8 offset:14080
	ds_read_b128 v[54:57], v8 offset:22016
	ds_read_b128 v[62:65], v8 offset:22272
	ds_read_b128 v[78:81], v8 offset:30208
	ds_read_b128 v[82:85], v8 offset:30464
	ds_read_b128 v[90:93], v8 offset:38400
	ds_read_b128 v[102:105], v8 offset:38656
	ds_read2_b32 v[120:121], v9 offset0:96 offset1:112
	ds_read_b64 v[124:125], v7 offset:43096
	v_pk_mul_f32 v[12:13], v[72:73], v[46:47]
	v_add_f32_dpp v58, v48, v48 quad_perm:[1,0,3,2] row_mask:0xf bank_mask:0xf bound_ctrl:1
	s_waitcnt lgkmcnt(15)
	v_pk_mul_f32 v[48:49], v[76:77], v[46:47]
	v_pk_fma_f32 v[0:1], v[10:11], v[2:3], v[0:1]
	v_pk_fma_f32 v[10:11], v[70:71], v[2:3], v[12:13]
	v_pk_mul_f32 v[38:39], v[38:39], v[2:3]
	v_pk_fma_f32 v[2:3], v[74:75], v[2:3], v[48:49]
	v_add_f32_e32 v0, v0, v1
	v_add_f32_e32 v1, v10, v11
	v_add_f32_e32 v2, v2, v3
	v_add_f32_dpp v0, v0, v0 quad_perm:[1,0,3,2] row_mask:0xf bank_mask:0xf bound_ctrl:1
	v_add_f32_dpp v1, v1, v1 quad_perm:[1,0,3,2] row_mask:0xf bank_mask:0xf bound_ctrl:1
	v_add_f32_dpp v2, v2, v2 quad_perm:[1,0,3,2] row_mask:0xf bank_mask:0xf bound_ctrl:1
	v_cndmask_b32_e32 v0, v0, v58, vcc
	v_add_f32_dpp v1, v1, v1 quad_perm:[2,3,0,1] row_mask:0xf bank_mask:0xf bound_ctrl:1
	v_add_f32_dpp v2, v2, v2 quad_perm:[2,3,0,1] row_mask:0xf bank_mask:0xf bound_ctrl:1
	v_add_f32_dpp v0, v0, v0 row_ror:2 row_mask:0xf bank_mask:0xf bound_ctrl:1
	v_add_f32_dpp v1, v1, v1 row_half_mirror row_mask:0xf bank_mask:0xf bound_ctrl:1
	v_pk_mul_f32 v[40:41], v[40:41], v[46:47]
	v_add_f32_dpp v2, v2, v2 row_half_mirror row_mask:0xf bank_mask:0xf bound_ctrl:1
	v_add_f32_dpp v0, v0, v0 row_ror:4 row_mask:0xf bank_mask:0xf bound_ctrl:1
	v_add_f32_dpp v107, v1, v1 row_mirror row_mask:0xf bank_mask:0xf bound_ctrl:1
	s_waitcnt lgkmcnt(13)
; template <int CTRL> __device__ __forceinline__ float dppf(float x) { return __builtin_bit_cast(float, __builtin_amdgcn_mov_dpp(__builtin_bit_cast(int, x), CTRL, 0xf, 0xf, true)); }
; __device__ __forceinline__ float dot4(const f32x4& a, const f32x4& b) {
;     f32x2 t = __builtin_shufflevector(a, a, 0, 1) * __builtin_shufflevector(b, b, 0, 1);
;     t = __builtin_shufflevector(a, a, 2, 3) * __builtin_shufflevector(b, b, 2, 3) + t;
;     return t[0] + t[1];
; }
; __device__ __forceinline__ void reduce16x2(float& a, float& b) {
;     a += dppf<0xB1>(a); b += dppf<0xB1>(b); a += dppf<0x4E>(a); b += dppf<0x4E>(b);
;     a += dppf<0x141>(a); b += dppf<0x141>(b); a += dppf<0x140>(a); b += dppf<0x140>(b);
; }
; __device__ __forceinline__ void scan_unit(const Params& p, int unit) {
;     ...
;             for (int pr = 0; pr < SC_TC / 2; ++pr) {
;                 const int sn = 2 * pr + 2;
;                 const f32x4 r1n = SC_LD(0, sn), w1n = SC_LD(1, sn), k1n = SC_LD(2, sn), q1n = SC_LD(3, sn), n1n = SC_LD(4, sn);
;                 const f32x4 r2n = SC_LD(0, sn + 1), w2n = SC_LD(1, sn + 1), k2n = SC_LD(2, sn + 1), g2n = SC_LD(3, sn + 1), n2n = SC_LD(4, sn + 1);
;                 const float v1n = buf[SC_VOFF + sn * 16 + rl], v2n = buf[SC_VOFF + (sn + 1) * 16 + rl];
;                 const f32x2 cfn = *(const f32x2*)(buf + SC_COFF + (pr + 1) * 2);
;                 __builtin_amdgcn_sched_barrier(0x7);
;                 float d1 = dot4(S, q1), e2 = dot4(S, g2);
;                 const f32x4 t1 = S * w1 + v1 * k1;
;                 reduce16x2(d1, e2);
;                 const float d2 = e2 + v1 * cf[0] - d1 * cf[1];
;                 const f32x4 S1 = t1 + d1 * n1;
;                 const f32x4 S2 = (S1 * w2 + v2 * k2) + d2 * n2;
;                 float y1 = dot4(S1, r1), y2 = dot4(S2, r2);
;                 y1 += dppf<0xB1>(y1); y2 += dppf<0xB1>(y2);
;                 float yz = odd_lane ? y2 : y1;
;                 yz += dppf<0x122>(yz); yz += dppf<0x124>(yz); yz += dppf<0x128>(yz);
;                 yb[(2 * pr) * 16 + yoff] = yz;
;                 S = S2;
;                 r1 = r1n; w1 = w1n; k1 = k1n; q1 = q1n; n1 = n1n; r2 = r2n; w2 = w2n; k2 = k2n; g2 = g2n; n2 = n2n; v1 = v1n; v2 = v2n; cf = cfn;
	v_mov_b32_e32 v106, v122
	v_pk_fma_f32 v[12:13], v[50:51], v[122:123], v[38:39] op_sel_hi:[1,0,1]
	v_pk_fma_f32 v[38:39], v[52:53], v[122:123], v[40:41] op_sel_hi:[1,0,1]
	v_add_f32_dpp v1, v2, v2 row_mirror row_mask:0xf bank_mask:0xf bound_ctrl:1
	v_add_f32_dpp v2, v0, v0 row_ror:8 row_mask:0xf bank_mask:0xf bound_ctrl:1
	v_mov_b32_e32 v0, v107
	v_pk_mul_f32 v[114:115], v[106:107], v[116:117]
	v_pk_fma_f32 v[106:107], v[88:89], v[0:1], v[38:39] op_sel_hi:[1,0,1]
	v_pk_fma_f32 v[116:117], v[86:87], v[0:1], v[12:13] op_sel_hi:[1,0,1]
	v_add_f32_e32 v109, v114, v1
	v_pk_mul_f32 v[42:43], v[42:43], v[116:117]
	v_pk_mul_f32 v[44:45], v[44:45], v[106:107]
	v_sub_f32_e32 v114, v109, v115
	v_pk_mul_f32 v[24:25], v[24:25], v[106:107]
	v_pk_fma_f32 v[44:45], v[68:69], v[122:123], v[44:45] op_sel:[0,1,0]
	v_pk_fma_f32 v[42:43], v[66:67], v[122:123], v[42:43] op_sel:[0,1,0]
	v_pk_fma_f32 v[22:23], v[22:23], v[116:117], v[24:25]
	v_pk_fma_f32 v[24:25], v[98:99], v[114:115], v[42:43] op_sel_hi:[1,0,1]
	v_pk_fma_f32 v[42:43], v[100:101], v[114:115], v[44:45] op_sel_hi:[1,0,1]
	v_add_f32_e32 v44, v22, v23
	v_pk_mul_f32 v[22:23], v[32:33], v[42:43]
	s_waitcnt lgkmcnt(5)
	ds_write_b32 v6, v2 offset:1152
	ds_read_b128 v[0:3], v8 offset:6144
	ds_read_b128 v[10:13], v8 offset:6400
	ds_read_b128 v[38:41], v8 offset:14336
	ds_read_b128 v[46:49], v8 offset:14592
	ds_read_b128 v[50:53], v8 offset:22528
	ds_read_b128 v[58:61], v8 offset:22784
	ds_read_b128 v[70:73], v8 offset:30720
	ds_read_b128 v[74:77], v8 offset:30976
	ds_read_b128 v[86:89], v8 offset:38912
	ds_read_b128 v[94:97], v8 offset:39168
	ds_read2_b32 v[118:119], v9 offset0:128 offset1:144
	ds_read_b64 v[122:123], v7 offset:43104
	v_pk_mul_f32 v[32:33], v[80:81], v[42:43]
	v_pk_fma_f32 v[22:23], v[30:31], v[24:25], v[22:23]
	v_pk_fma_f32 v[30:31], v[78:79], v[24:25], v[32:33]
	v_add_f32_dpp v66, v44, v44 quad_perm:[1,0,3,2] row_mask:0xf bank_mask:0xf bound_ctrl:1
	s_waitcnt lgkmcnt(15)
	v_pk_mul_f32 v[44:45], v[84:85], v[42:43]
	v_add_f32_e32 v22, v22, v23
	v_add_f32_e32 v23, v30, v31
	v_pk_mul_f32 v[26:27], v[26:27], v[24:25]
	v_pk_fma_f32 v[24:25], v[82:83], v[24:25], v[44:45]
	v_add_f32_dpp v22, v22, v22 quad_perm:[1,0,3,2] row_mask:0xf bank_mask:0xf bound_ctrl:1
	v_add_f32_dpp v23, v23, v23 quad_perm:[1,0,3,2] row_mask:0xf bank_mask:0xf bound_ctrl:1
	v_add_f32_e32 v24, v24, v25
	v_cndmask_b32_e32 v22, v22, v66, vcc
	v_add_f32_dpp v23, v23, v23 quad_perm:[2,3,0,1] row_mask:0xf bank_mask:0xf bound_ctrl:1
	v_add_f32_dpp v24, v24, v24 quad_perm:[1,0,3,2] row_mask:0xf bank_mask:0xf bound_ctrl:1
	v_add_f32_dpp v22, v22, v22 row_ror:2 row_mask:0xf bank_mask:0xf bound_ctrl:1
	v_add_f32_dpp v23, v23, v23 row_half_mirror row_mask:0xf bank_mask:0xf bound_ctrl:1
	v_pk_mul_f32 v[28:29], v[28:29], v[42:43]
	v_add_f32_dpp v24, v24, v24 quad_perm:[2,3,0,1] row_mask:0xf bank_mask:0xf bound_ctrl:1
	v_add_f32_dpp v22, v22, v22 row_ror:4 row_mask:0xf bank_mask:0xf bound_ctrl:1
	v_add_f32_dpp v111, v23, v23 row_mirror row_mask:0xf bank_mask:0xf bound_ctrl:1
	s_waitcnt lgkmcnt(14)
	v_mov_b32_e32 v110, v120
	v_pk_fma_f32 v[26:27], v[54:55], v[120:121], v[26:27] op_sel_hi:[1,0,1]
	v_pk_fma_f32 v[28:29], v[56:57], v[120:121], v[28:29] op_sel_hi:[1,0,1]
	v_add_f32_dpp v24, v24, v24 row_half_mirror row_mask:0xf bank_mask:0xf bound_ctrl:1
	v_add_f32_dpp v23, v22, v22 row_ror:8 row_mask:0xf bank_mask:0xf bound_ctrl:1
	v_mov_b32_e32 v22, v111
	v_mov_b32_e32 v112, v121
	v_add_f32_dpp v107, v24, v24 row_mirror row_mask:0xf bank_mask:0xf bound_ctrl:1
	s_waitcnt lgkmcnt(13)
	v_pk_mul_f32 v[110:111], v[110:111], v[124:125]
	v_pk_fma_f32 v[120:121], v[92:93], v[22:23], v[28:29] op_sel_hi:[1,0,1]
	v_pk_fma_f32 v[124:125], v[90:91], v[22:23], v[26:27] op_sel_hi:[1,0,1]
	v_add_f32_e32 v107, v110, v107
	v_pk_mul_f32 v[34:35], v[34:35], v[124:125]
	v_pk_mul_f32 v[36:37], v[36:37], v[120:121]
	v_pk_mul_f32 v[16:17], v[16:17], v[120:121]
	v_sub_f32_e32 v110, v107, v111
	v_pk_fma_f32 v[36:37], v[64:65], v[112:113], v[36:37] op_sel_hi:[1,0,1]
	v_pk_fma_f32 v[34:35], v[62:63], v[112:113], v[34:35] op_sel_hi:[1,0,1]
	v_pk_fma_f32 v[14:15], v[14:15], v[124:125], v[16:17]
	v_pk_fma_f32 v[16:17], v[102:103], v[110:111], v[34:35] op_sel_hi:[1,0,1]
	v_pk_fma_f32 v[34:35], v[104:105], v[110:111], v[36:37] op_sel_hi:[1,0,1]
	v_add_f32_e32 v36, v14, v15
	v_pk_mul_f32 v[14:15], v[20:21], v[34:35]
	s_waitcnt lgkmcnt(5)
	v_pk_mul_f32 v[20:21], v[72:73], v[34:35]
	v_add_f32_dpp v62, v36, v36 quad_perm:[1,0,3,2] row_mask:0xf bank_mask:0xf bound_ctrl:1
	s_waitcnt lgkmcnt(4)
	ds_write_b32 v6, v23 offset:1280
	ds_read_b64 v[114:115], v7 offset:43112
	ds_read_b64 v[116:117], v7 offset:43120
	ds_read_b128 v[22:25], v8 offset:6656
	ds_read_b128 v[26:29], v8 offset:6912
	ds_read_b128 v[30:33], v8 offset:14848
	ds_read_b128 v[42:45], v8 offset:15104
	ds_read_b128 v[54:57], v8 offset:23040
	ds_read_b128 v[66:69], v8 offset:23296
	ds_read_b128 v[78:81], v8 offset:31232
	ds_read_b128 v[82:85], v8 offset:31488
	ds_read_b128 v[90:93], v8 offset:39424
	ds_read_b128 v[98:101], v8 offset:39680
	ds_read2_b32 v[126:127], v9 offset0:160 offset1:176
	v_pk_mul_f32 v[36:37], v[76:77], v[34:35]
	v_pk_fma_f32 v[14:15], v[18:19], v[16:17], v[14:15]
	v_pk_fma_f32 v[18:19], v[70:71], v[16:17], v[20:21]
	v_pk_mul_f32 v[38:39], v[38:39], v[16:17]
	v_pk_fma_f32 v[16:17], v[74:75], v[16:17], v[36:37]
	v_add_f32_e32 v14, v14, v15
	v_add_f32_e32 v15, v18, v19
	v_add_f32_e32 v16, v16, v17
	v_add_f32_dpp v14, v14, v14 quad_perm:[1,0,3,2] row_mask:0xf bank_mask:0xf bound_ctrl:1
	v_add_f32_dpp v15, v15, v15 quad_perm:[1,0,3,2] row_mask:0xf bank_mask:0xf bound_ctrl:1
	v_add_f32_dpp v16, v16, v16 quad_perm:[1,0,3,2] row_mask:0xf bank_mask:0xf bound_ctrl:1
	v_cndmask_b32_e32 v14, v14, v62, vcc
	v_add_f32_dpp v15, v15, v15 quad_perm:[2,3,0,1] row_mask:0xf bank_mask:0xf bound_ctrl:1
	v_add_f32_dpp v16, v16, v16 quad_perm:[2,3,0,1] row_mask:0xf bank_mask:0xf bound_ctrl:1
	v_add_f32_dpp v14, v14, v14 row_ror:2 row_mask:0xf bank_mask:0xf bound_ctrl:1
	v_add_f32_dpp v15, v15, v15 row_half_mirror row_mask:0xf bank_mask:0xf bound_ctrl:1
	v_pk_mul_f32 v[34:35], v[40:41], v[34:35]
	v_add_f32_dpp v16, v16, v16 row_half_mirror row_mask:0xf bank_mask:0xf bound_ctrl:1
	v_add_f32_dpp v14, v14, v14 row_ror:4 row_mask:0xf bank_mask:0xf bound_ctrl:1
	v_add_f32_dpp v107, v15, v15 row_mirror row_mask:0xf bank_mask:0xf bound_ctrl:1
	s_waitcnt lgkmcnt(15)
; template <int CTRL> __device__ __forceinline__ float dppf(float x) { return __builtin_bit_cast(float, __builtin_amdgcn_mov_dpp(__builtin_bit_cast(int, x), CTRL, 0xf, 0xf, true)); }
; __device__ __forceinline__ void scan_unit(const Params& p, int unit) {
;     ...
;             f32x4 r1 = SC_LD(0, 0), w1 = SC_LD(1, 0), k1 = SC_LD(2, 0), q1 = SC_LD(3, 0), n1 = SC_LD(4, 0);
;             f32x4 r2 = SC_LD(0, 1), w2 = SC_LD(1, 1), k2 = SC_LD(2, 1), g2 = SC_LD(3, 1), n2 = SC_LD(4, 1);
;             float v1 = buf[SC_VOFF + rl], v2 = buf[SC_VOFF + 16 + rl];
;             f32x2 cf = *(const f32x2*)(buf + SC_COFF);
; #pragma unroll
;             for (int pr = 0; pr < SC_TC / 2; ++pr) {
;                 const int sn = 2 * pr + 2;
;                 const f32x4 r1n = SC_LD(0, sn), w1n = SC_LD(1, sn), k1n = SC_LD(2, sn), q1n = SC_LD(3, sn), n1n = SC_LD(4, sn);
;                 const f32x4 r2n = SC_LD(0, sn + 1), w2n = SC_LD(1, sn + 1), k2n = SC_LD(2, sn + 1), g2n = SC_LD(3, sn + 1), n2n = SC_LD(4, sn + 1);
;                 const float v1n = buf[SC_VOFF + sn * 16 + rl], v2n = buf[SC_VOFF + (sn + 1) * 16 + rl];
;                 const f32x2 cfn = *(const f32x2*)(buf + SC_COFF + (pr + 1) * 2);
;                 __builtin_amdgcn_sched_barrier(0x7);
;                 float d1 = dot4(S, q1), e2 = dot4(S, g2);
;                 const f32x4 t1 = S * w1 + v1 * k1;
;                 reduce16x2(d1, e2);
;                 const float d2 = e2 + v1 * cf[0] - d1 * cf[1];
;                 const f32x4 S1 = t1 + d1 * n1;
;                 const f32x4 S2 = (S1 * w2 + v2 * k2) + d2 * n2;
;                 float y1 = dot4(S1, r1), y2 = dot4(S2, r2);
;                 y1 += dppf<0xB1>(y1); y2 += dppf<0xB1>(y2);
;                 float yz = odd_lane ? y2 : y1;
;                 yz += dppf<0x122>(yz); yz += dppf<0x124>(yz); yz += dppf<0x128>(yz);
;                 yb[(2 * pr) * 16 + yoff] = yz;
;                 S = S2;
;                 r1 = r1n; w1 = w1n; k1 = k1n; q1 = q1n; n1 = n1n; r2 = r2n; w2 = w2n; k2 = k2n; g2 = g2n; n2 = n2n; v1 = v1n; v2 = v2n; cf = cfn;
;             }
	v_mov_b32_e32 v106, v118
	v_pk_fma_f32 v[20:21], v[50:51], v[118:119], v[38:39] op_sel_hi:[1,0,1]
	v_pk_fma_f32 v[34:35], v[52:53], v[118:119], v[34:35] op_sel_hi:[1,0,1]
	v_add_f32_dpp v15, v16, v16 row_mirror row_mask:0xf bank_mask:0xf bound_ctrl:1
	v_add_f32_dpp v16, v14, v14 row_ror:8 row_mask:0xf bank_mask:0xf bound_ctrl:1
	v_mov_b32_e32 v14, v107
	v_mov_b32_e32 v108, v119
	s_waitcnt lgkmcnt(14)
	v_pk_mul_f32 v[118:119], v[106:107], v[122:123]
	v_pk_fma_f32 v[106:107], v[88:89], v[14:15], v[34:35] op_sel_hi:[1,0,1]
	v_pk_fma_f32 v[120:121], v[86:87], v[14:15], v[20:21] op_sel_hi:[1,0,1]
	v_add_f32_e32 v109, v118, v15
	v_pk_mul_f32 v[46:47], v[46:47], v[120:121]
	v_pk_mul_f32 v[48:49], v[48:49], v[106:107]
	v_sub_f32_e32 v118, v109, v119
	v_pk_mul_f32 v[2:3], v[2:3], v[106:107]
	v_pk_fma_f32 v[48:49], v[60:61], v[108:109], v[48:49] op_sel_hi:[1,0,1]
	v_pk_fma_f32 v[46:47], v[58:59], v[108:109], v[46:47] op_sel_hi:[1,0,1]
	v_pk_fma_f32 v[0:1], v[0:1], v[120:121], v[2:3]
	v_pk_fma_f32 v[2:3], v[94:95], v[118:119], v[46:47] op_sel_hi:[1,0,1]
	v_pk_fma_f32 v[46:47], v[96:97], v[118:119], v[48:49] op_sel_hi:[1,0,1]
	v_add_f32_e32 v48, v0, v1
	v_pk_mul_f32 v[0:1], v[12:13], v[46:47]
	s_waitcnt lgkmcnt(4)
	ds_write_b32 v6, v16 offset:1408
	ds_read_b128 v[14:17], v8 offset:7168
	ds_read_b128 v[18:21], v8 offset:7424
	ds_read_b128 v[34:37], v8 offset:15360
	ds_read_b128 v[38:41], v8 offset:15616
	ds_read_b128 v[50:53], v8 offset:23552
	ds_read_b128 v[62:65], v8 offset:23808
	ds_read_b128 v[70:73], v8 offset:31744
	ds_read_b128 v[74:77], v8 offset:32000
	ds_read_b128 v[86:89], v8 offset:39936
	ds_read_b128 v[102:105], v8 offset:40192
	ds_read2_b32 v[122:123], v9 offset0:192 offset1:208
	v_pk_mul_f32 v[12:13], v[80:81], v[46:47]
	v_add_f32_dpp v58, v48, v48 quad_perm:[1,0,3,2] row_mask:0xf bank_mask:0xf bound_ctrl:1
	s_waitcnt lgkmcnt(15)
	v_pk_mul_f32 v[48:49], v[84:85], v[46:47]
	v_pk_fma_f32 v[0:1], v[10:11], v[2:3], v[0:1]
	v_pk_fma_f32 v[10:11], v[78:79], v[2:3], v[12:13]
	v_pk_mul_f32 v[30:31], v[30:31], v[2:3]
	v_pk_fma_f32 v[2:3], v[82:83], v[2:3], v[48:49]
	v_add_f32_e32 v0, v0, v1
	v_add_f32_e32 v1, v10, v11
	v_add_f32_e32 v2, v2, v3
	v_add_f32_dpp v0, v0, v0 quad_perm:[1,0,3,2] row_mask:0xf bank_mask:0xf bound_ctrl:1
	v_add_f32_dpp v1, v1, v1 quad_perm:[1,0,3,2] row_mask:0xf bank_mask:0xf bound_ctrl:1
	v_add_f32_dpp v2, v2, v2 quad_perm:[1,0,3,2] row_mask:0xf bank_mask:0xf bound_ctrl:1
	v_cndmask_b32_e32 v0, v0, v58, vcc
	v_add_f32_dpp v1, v1, v1 quad_perm:[2,3,0,1] row_mask:0xf bank_mask:0xf bound_ctrl:1
	v_add_f32_dpp v2, v2, v2 quad_perm:[2,3,0,1] row_mask:0xf bank_mask:0xf bound_ctrl:1
	v_add_f32_dpp v0, v0, v0 row_ror:2 row_mask:0xf bank_mask:0xf bound_ctrl:1
	v_add_f32_dpp v1, v1, v1 row_half_mirror row_mask:0xf bank_mask:0xf bound_ctrl:1
	v_pk_mul_f32 v[32:33], v[32:33], v[46:47]
	v_add_f32_dpp v2, v2, v2 row_half_mirror row_mask:0xf bank_mask:0xf bound_ctrl:1
	v_add_f32_dpp v0, v0, v0 row_ror:4 row_mask:0xf bank_mask:0xf bound_ctrl:1
	v_add_f32_dpp v111, v1, v1 row_mirror row_mask:0xf bank_mask:0xf bound_ctrl:1
	s_waitcnt lgkmcnt(12)
	v_mov_b32_e32 v110, v126
	v_pk_fma_f32 v[12:13], v[54:55], v[126:127], v[30:31] op_sel_hi:[1,0,1]
	v_pk_fma_f32 v[30:31], v[56:57], v[126:127], v[32:33] op_sel_hi:[1,0,1]
	v_add_f32_dpp v1, v2, v2 row_mirror row_mask:0xf bank_mask:0xf bound_ctrl:1
	v_add_f32_dpp v2, v0, v0 row_ror:8 row_mask:0xf bank_mask:0xf bound_ctrl:1
	v_mov_b32_e32 v0, v111
	v_pk_mul_f32 v[114:115], v[110:111], v[114:115]
	v_pk_fma_f32 v[110:111], v[92:93], v[0:1], v[30:31] op_sel_hi:[1,0,1]
	v_pk_fma_f32 v[118:119], v[90:91], v[0:1], v[12:13] op_sel_hi:[1,0,1]
	v_mov_b32_e32 v112, v127
	v_add_f32_e32 v107, v114, v1
	v_pk_mul_f32 v[42:43], v[42:43], v[118:119]
	v_pk_mul_f32 v[44:45], v[44:45], v[110:111]
	v_sub_f32_e32 v114, v107, v115
	v_pk_mul_f32 v[24:25], v[24:25], v[110:111]
	v_pk_fma_f32 v[44:45], v[68:69], v[112:113], v[44:45] op_sel_hi:[1,0,1]
	v_pk_fma_f32 v[42:43], v[66:67], v[112:113], v[42:43] op_sel_hi:[1,0,1]
	ds_write_b32 v6, v2 offset:1536
	v_pk_fma_f32 v[22:23], v[22:23], v[118:119], v[24:25]
	v_pk_fma_f32 v[24:25], v[98:99], v[114:115], v[42:43] op_sel_hi:[1,0,1]
	v_pk_fma_f32 v[42:43], v[100:101], v[114:115], v[44:45] op_sel_hi:[1,0,1]
	ds_read_b128 v[0:3], v8 offset:7680
	ds_read_b128 v[10:13], v8 offset:7936
	ds_read_b128 v[30:33], v8 offset:15872
	ds_read_b128 v[46:49], v8 offset:16128
	ds_read_b128 v[54:57], v8 offset:24064
	ds_read_b128 v[58:61], v8 offset:24320
	ds_read_b128 v[78:81], v8 offset:32256
	ds_read_b128 v[82:85], v8 offset:32512
	ds_read_b128 v[90:93], v8 offset:40448
	ds_read_b128 v[94:97], v8 offset:40704
	ds_read2_b32 v[8:9], v9 offset0:224 offset1:240
	ds_read_b64 v[120:121], v7 offset:43128
	v_add_f32_e32 v7, v22, v23
	v_pk_mul_f32 v[22:23], v[28:29], v[42:43]
	s_waitcnt lgkmcnt(14)
; template <int CTRL> __device__ __forceinline__ float dppf(float x) { return __builtin_bit_cast(float, __builtin_amdgcn_mov_dpp(__builtin_bit_cast(int, x), CTRL, 0xf, 0xf, true)); }
; __device__ __forceinline__ void scan_unit(const Params& p, int unit) {
;     ...
;             for (int pr = 0; pr < SC_TC / 2; ++pr) {
;                 const int sn = 2 * pr + 2;
;                 const f32x4 r1n = SC_LD(0, sn), w1n = SC_LD(1, sn), k1n = SC_LD(2, sn), q1n = SC_LD(3, sn), n1n = SC_LD(4, sn);
;                 const f32x4 r2n = SC_LD(0, sn + 1), w2n = SC_LD(1, sn + 1), k2n = SC_LD(2, sn + 1), g2n = SC_LD(3, sn + 1), n2n = SC_LD(4, sn + 1);
;                 const float v1n = buf[SC_VOFF + sn * 16 + rl], v2n = buf[SC_VOFF + (sn + 1) * 16 + rl];
;                 const f32x2 cfn = *(const f32x2*)(buf + SC_COFF + (pr + 1) * 2);
;                 __builtin_amdgcn_sched_barrier(0x7);
;                 float d1 = dot4(S, q1), e2 = dot4(S, g2);
;                 const f32x4 t1 = S * w1 + v1 * k1;
;                 reduce16x2(d1, e2);
;                 const float d2 = e2 + v1 * cf[0] - d1 * cf[1];
;                 const f32x4 S1 = t1 + d1 * n1;
;                 const f32x4 S2 = (S1 * w2 + v2 * k2) + d2 * n2;
;                 float y1 = dot4(S1, r1), y2 = dot4(S2, r2);
;                 y1 += dppf<0xB1>(y1); y2 += dppf<0xB1>(y2);
;                 float yz = odd_lane ? y2 : y1;
;                 yz += dppf<0x122>(yz); yz += dppf<0x124>(yz); yz += dppf<0x128>(yz);
;                 yb[(2 * pr) * 16 + yoff] = yz;
;                 S = S2;
;                 r1 = r1n; w1 = w1n; k1 = k1n; q1 = q1n; n1 = n1n; r2 = r2n; w2 = w2n; k2 = k2n; g2 = g2n; n2 = n2n; v1 = v1n; v2 = v2n; cf = cfn;
;             }
;     ...
;             __syncthreads();
;         }
;         __builtin_amdgcn_s_setprio(0);
	v_pk_mul_f32 v[28:29], v[72:73], v[42:43]
	v_pk_mul_f32 v[44:45], v[76:77], v[42:43]
	v_pk_fma_f32 v[22:23], v[26:27], v[24:25], v[22:23]
	v_pk_fma_f32 v[26:27], v[70:71], v[24:25], v[28:29]
	v_pk_mul_f32 v[34:35], v[34:35], v[24:25]
	v_pk_fma_f32 v[24:25], v[74:75], v[24:25], v[44:45]
	v_add_f32_e32 v22, v22, v23
	v_add_f32_e32 v23, v26, v27
	v_add_f32_dpp v7, v7, v7 quad_perm:[1,0,3,2] row_mask:0xf bank_mask:0xf bound_ctrl:1
	v_add_f32_e32 v24, v24, v25
	v_add_f32_dpp v22, v22, v22 quad_perm:[1,0,3,2] row_mask:0xf bank_mask:0xf bound_ctrl:1
	v_add_f32_dpp v23, v23, v23 quad_perm:[1,0,3,2] row_mask:0xf bank_mask:0xf bound_ctrl:1
	v_add_f32_dpp v24, v24, v24 quad_perm:[1,0,3,2] row_mask:0xf bank_mask:0xf bound_ctrl:1
	v_cndmask_b32_e32 v7, v22, v7, vcc
	v_add_f32_dpp v22, v23, v23 quad_perm:[2,3,0,1] row_mask:0xf bank_mask:0xf bound_ctrl:1
	v_add_f32_dpp v23, v24, v24 quad_perm:[2,3,0,1] row_mask:0xf bank_mask:0xf bound_ctrl:1
	v_add_f32_dpp v7, v7, v7 row_ror:2 row_mask:0xf bank_mask:0xf bound_ctrl:1
	v_add_f32_dpp v22, v22, v22 row_half_mirror row_mask:0xf bank_mask:0xf bound_ctrl:1
	s_waitcnt lgkmcnt(13)
	v_mov_b32_e32 v106, v122
	v_pk_mul_f32 v[36:37], v[36:37], v[42:43]
	v_add_f32_dpp v23, v23, v23 row_half_mirror row_mask:0xf bank_mask:0xf bound_ctrl:1
	v_add_f32_dpp v7, v7, v7 row_ror:4 row_mask:0xf bank_mask:0xf bound_ctrl:1
	v_add_f32_dpp v107, v22, v22 row_mirror row_mask:0xf bank_mask:0xf bound_ctrl:1
	v_pk_fma_f32 v[28:29], v[50:51], v[122:123], v[34:35] op_sel_hi:[1,0,1]
	v_pk_fma_f32 v[34:35], v[52:53], v[122:123], v[36:37] op_sel_hi:[1,0,1]
	v_add_f32_dpp v25, v23, v23 row_mirror row_mask:0xf bank_mask:0xf bound_ctrl:1
	v_add_f32_dpp v7, v7, v7 row_ror:8 row_mask:0xf bank_mask:0xf bound_ctrl:1
	v_pk_mul_f32 v[22:23], v[106:107], v[116:117]
	ds_write_b32 v6, v7 offset:1664
	v_add_f32_e32 v7, v22, v25
	v_pk_fma_f32 v[26:27], v[88:89], v[106:107], v[34:35] op_sel:[0,1,0]
	v_pk_fma_f32 v[24:25], v[86:87], v[106:107], v[28:29] op_sel:[0,1,0]
	v_mov_b32_e32 v108, v123
	v_pk_mul_f32 v[28:29], v[38:39], v[24:25]
	v_pk_mul_f32 v[34:35], v[40:41], v[26:27]
	v_sub_f32_e32 v22, v7, v23
	v_pk_mul_f32 v[16:17], v[16:17], v[26:27]
	v_pk_fma_f32 v[26:27], v[64:65], v[108:109], v[34:35] op_sel_hi:[1,0,1]
	v_pk_fma_f32 v[28:29], v[62:63], v[108:109], v[28:29] op_sel_hi:[1,0,1]
	v_pk_fma_f32 v[14:15], v[14:15], v[24:25], v[16:17]
	v_pk_fma_f32 v[16:17], v[102:103], v[22:23], v[28:29] op_sel_hi:[1,0,1]
	v_pk_fma_f32 v[22:23], v[104:105], v[22:23], v[26:27] op_sel_hi:[1,0,1]
	v_add_f32_e32 v7, v14, v15
	v_pk_mul_f32 v[14:15], v[20:21], v[22:23]
	s_waitcnt lgkmcnt(6)
	v_pk_mul_f32 v[20:21], v[80:81], v[22:23]
	s_waitcnt lgkmcnt(5)
	v_pk_mul_f32 v[24:25], v[84:85], v[22:23]
	v_pk_fma_f32 v[14:15], v[18:19], v[16:17], v[14:15]
	v_pk_fma_f32 v[18:19], v[78:79], v[16:17], v[20:21]
	v_pk_mul_f32 v[26:27], v[30:31], v[16:17]
	v_pk_fma_f32 v[16:17], v[82:83], v[16:17], v[24:25]
	v_add_f32_e32 v14, v14, v15
	v_add_f32_e32 v15, v18, v19
	v_add_f32_dpp v7, v7, v7 quad_perm:[1,0,3,2] row_mask:0xf bank_mask:0xf bound_ctrl:1
	v_add_f32_e32 v16, v16, v17
	v_add_f32_dpp v14, v14, v14 quad_perm:[1,0,3,2] row_mask:0xf bank_mask:0xf bound_ctrl:1
	v_add_f32_dpp v15, v15, v15 quad_perm:[1,0,3,2] row_mask:0xf bank_mask:0xf bound_ctrl:1
	v_add_f32_dpp v16, v16, v16 quad_perm:[1,0,3,2] row_mask:0xf bank_mask:0xf bound_ctrl:1
	v_cndmask_b32_e32 v7, v14, v7, vcc
	v_add_f32_dpp v14, v15, v15 quad_perm:[2,3,0,1] row_mask:0xf bank_mask:0xf bound_ctrl:1
	v_add_f32_dpp v15, v16, v16 quad_perm:[2,3,0,1] row_mask:0xf bank_mask:0xf bound_ctrl:1
	v_pk_mul_f32 v[22:23], v[32:33], v[22:23]
	v_add_f32_dpp v14, v14, v14 row_half_mirror row_mask:0xf bank_mask:0xf bound_ctrl:1
	v_add_f32_dpp v7, v7, v7 row_ror:2 row_mask:0xf bank_mask:0xf bound_ctrl:1
	v_add_f32_dpp v15, v15, v15 row_half_mirror row_mask:0xf bank_mask:0xf bound_ctrl:1
	v_add_f32_dpp v37, v14, v14 row_mirror row_mask:0xf bank_mask:0xf bound_ctrl:1
	s_waitcnt lgkmcnt(2)
	v_mov_b32_e32 v36, v8
	v_mov_b32_e32 v42, v9
	v_pk_fma_f32 v[20:21], v[54:55], v[8:9], v[26:27] op_sel_hi:[1,0,1]
	v_pk_fma_f32 v[8:9], v[56:57], v[8:9], v[22:23] op_sel_hi:[1,0,1]
	v_add_f32_dpp v7, v7, v7 row_ror:4 row_mask:0xf bank_mask:0xf bound_ctrl:1
	v_add_f32_dpp v17, v15, v15 row_mirror row_mask:0xf bank_mask:0xf bound_ctrl:1
	v_add_f32_dpp v7, v7, v7 row_ror:8 row_mask:0xf bank_mask:0xf bound_ctrl:1
	s_waitcnt lgkmcnt(1)
	v_pk_mul_f32 v[14:15], v[36:37], v[120:121]
	v_pk_fma_f32 v[8:9], v[92:93], v[36:37], v[8:9] op_sel:[0,1,0]
	ds_write_b32 v6, v7 offset:1792
	v_add_f32_e32 v7, v14, v17
	v_pk_fma_f32 v[16:17], v[90:91], v[36:37], v[20:21] op_sel:[0,1,0]
	v_pk_mul_f32 v[20:21], v[48:49], v[8:9]
	v_sub_f32_e32 v14, v7, v15
	v_pk_mul_f32 v[18:19], v[46:47], v[16:17]
	v_pk_mul_f32 v[2:3], v[2:3], v[8:9]
	v_pk_fma_f32 v[8:9], v[60:61], v[42:43], v[20:21] op_sel_hi:[1,0,1]
	v_pk_fma_f32 v[18:19], v[58:59], v[42:43], v[18:19] op_sel_hi:[1,0,1]
	v_pk_fma_f32 v[16:17], v[0:1], v[16:17], v[2:3]
	v_pk_fma_f32 v[2:3], v[96:97], v[14:15], v[8:9] op_sel_hi:[1,0,1]
	v_pk_fma_f32 v[0:1], v[94:95], v[14:15], v[18:19] op_sel_hi:[1,0,1]
	v_pk_mul_f32 v[8:9], v[12:13], v[2:3]
	v_add_f32_e32 v7, v16, v17
	v_pk_fma_f32 v[8:9], v[10:11], v[0:1], v[8:9]
	s_add_i32 s4, s4, 1
	v_add_f32_e32 v8, v8, v9
	v_add_f32_dpp v7, v7, v7 quad_perm:[1,0,3,2] row_mask:0xf bank_mask:0xf bound_ctrl:1
	s_cmpk_eq_i32 s4, 0x101
	v_add_f32_dpp v8, v8, v8 quad_perm:[1,0,3,2] row_mask:0xf bank_mask:0xf bound_ctrl:1
	v_cndmask_b32_e32 v7, v8, v7, vcc
	s_nop 1
	v_add_f32_dpp v7, v7, v7 row_ror:2 row_mask:0xf bank_mask:0xf bound_ctrl:1
	s_nop 1
	v_add_f32_dpp v7, v7, v7 row_ror:4 row_mask:0xf bank_mask:0xf bound_ctrl:1
	s_nop 1
	v_add_f32_dpp v7, v7, v7 row_ror:8 row_mask:0xf bank_mask:0xf bound_ctrl:1
	ds_write_b32 v6, v7 offset:1920
	s_waitcnt lgkmcnt(0)
	s_barrier
	s_cbranch_scc0 .LBB0_786
	s_setprio 0

; __device__ __forceinline__ unsigned pk_bf16(float lo, float hi) { const f32x2 v = {lo, hi}; return __builtin_bit_cast(unsigned, __builtin_convertvector(v, b16x2)); }
; __device__ __forceinline__ float sigmoidf_(float x) { return __builtin_amdgcn_rcpf(1.0f + __expf(-x)); }
;     __device__ __forceinline__ void row(int r, int col32, int fq, const f32x4& a00, const f32x4& a01, const f32x4& a10, const f32x4& a11) const { half(r, col32, fq, a00, a01); half(r, col32 + HALF, fq, a10, a11); }
;     __device__ __forceinline__ void row(int r, int col32, int fq, const f32x4& a00, const f32x4& a01, const f32x4& a10, const f32x4& a11) const { half(r, col32, fq, a00, a01); half(r, col32 + HALF, fq, a10, a11); }
;     __device__ __forceinline__ void row(int r, int col32, int fq, const f32x4& a00, const f32x4& a01, const f32x4& a10, const f32x4& a11) const { half(r, col32, fq, a00, a01); half(r, col32 + HALF, fq, a10, a11); }
;     __device__ __forceinline__ void row(int r, int col32, int fq, const f32x4& g0, const f32x4& g1, const f32x4& u0, const f32x4& u1) const {
;         float o[8];
; #pragma unroll
;         for (int j = 0; j < 4; ++j) { o[j] = g0[j] * sigmoidf_(g0[j]) * u0[j]; o[4 + j] = g1[j] * sigmoidf_(g1[j]) * u1[j]; }
;         u32x4 w; w.x = pk_bf16(o[0], o[1]); w.y = pk_bf16(o[2], o[3]); w.z = pk_bf16(o[4], o[5]); w.w = pk_bf16(o[6], o[7]);
;         const int pn = col32 >> 8, cin = (col32 & 255) + 8 * fq;
;         *(u32x4*)(act + (size_t)r * DFF + pn * 128 + cin) = w;
;     }
.LBB0_1249:
	v_mul_f32_e32 v154, 0xbfb8aa3b, v124
	v_mul_f32_e32 v155, 0xbfb8aa3b, v120
	v_mul_f32_e32 v165, 0xbfb8aa3b, v125
	v_exp_f32_e32 v154, v154
	v_exp_f32_e32 v155, v155
	v_exp_f32_e32 v165, v165
	s_lshl_b32 s26, s55, 7
	v_add_f32_e32 v154, 1.0, v154
	v_add_f32_e32 v166, 1.0, v155
	v_add_f32_e32 v155, 1.0, v165
	v_rcp_f32_e32 v154, v154
	v_rcp_f32_e32 v155, v155
	v_mul_f32_e32 v165, 0xbfb8aa3b, v121
	v_exp_f32_e32 v165, v165
	v_rcp_f32_e32 v166, v166
	v_pk_mul_f32 v[124:125], v[124:125], v[154:155]
	v_mul_f32_e32 v154, 0xbfb8aa3b, v127
	v_pk_mul_f32 v[116:117], v[124:125], v[116:117]
	v_add_f32_e32 v124, 1.0, v165
	v_mul_f32_e32 v125, 0xbfb8aa3b, v122
	v_rcp_f32_e32 v167, v124
	v_mul_f32_e32 v124, 0xbfb8aa3b, v126
	v_exp_f32_e32 v125, v125
	v_exp_f32_e32 v124, v124
	v_exp_f32_e32 v155, v154
	v_mul_f32_e32 v154, 0xbfb8aa3b, v123
	v_exp_f32_e32 v165, v154
	v_add_f32_e32 v125, 1.0, v125
	v_add_f32_e32 v124, 1.0, v124
	v_rcp_f32_e32 v154, v125
	v_add_f32_e32 v125, 1.0, v155
	v_rcp_f32_e32 v124, v124
	v_rcp_f32_e32 v125, v125
	v_add_f32_e32 v155, 1.0, v165
	v_rcp_f32_e32 v155, v155
	v_pk_mul_f32 v[120:121], v[120:121], v[166:167]
	s_ashr_i32 s27, s26, 31
	v_pk_mul_f32 v[120:121], v[120:121], v[112:113]
	v_pk_mul_f32 v[112:113], v[126:127], v[124:125]
	v_lshl_add_u32 v153, s24, 8, v148
	v_pk_mul_f32 v[118:119], v[112:113], v[118:119]
	v_pk_mul_f32 v[112:113], v[122:123], v[154:155]
	v_lshl_add_u64 v[146:147], s[26:27], 1, v[132:133]
	v_pk_mul_f32 v[122:123], v[112:113], v[114:115]
	v_cvt_pk_bf16_f32 v112, v116, v117
	v_cvt_pk_bf16_f32 v113, v118, v119
	v_cvt_pk_bf16_f32 v114, v120, v121
	v_cvt_pk_bf16_f32 v115, v122, v123
	v_mad_i64_i32 v[116:117], s[26:27], v153, s54, v[146:147]
	global_store_dwordx4 v[116:117], v[112:115], off nt
	v_or_b32_e32 v116, 16, v153
	s_andn2_b64 vcc, exec, s[6:7]
	v_mul_f32_e32 v112, 0xbfb8aa3b, v108
	v_mul_f32_e32 v113, 0xbfb8aa3b, v104
	v_mul_f32_e32 v114, 0xbfb8aa3b, v109
	v_exp_f32_e32 v112, v112
	v_exp_f32_e32 v113, v113
	v_exp_f32_e32 v114, v114
	s_mov_b64 s[6:7], -1
	v_add_f32_e32 v112, 1.0, v112
	v_add_f32_e32 v115, 1.0, v113
	v_add_f32_e32 v113, 1.0, v114
	v_rcp_f32_e32 v112, v112
	v_rcp_f32_e32 v113, v113
	v_mul_f32_e32 v114, 0xbfb8aa3b, v105
	v_exp_f32_e32 v117, v114
	v_rcp_f32_e32 v114, v115
	v_pk_mul_f32 v[108:109], v[108:109], v[112:113]
	v_mul_f32_e32 v112, 0xbfb8aa3b, v111
	v_pk_mul_f32 v[100:101], v[108:109], v[100:101]
	v_add_f32_e32 v108, 1.0, v117
	v_rcp_f32_e32 v115, v108
	v_mul_f32_e32 v109, 0xbfb8aa3b, v106
	v_mul_f32_e32 v108, 0xbfb8aa3b, v110
	v_exp_f32_e32 v109, v109
	v_exp_f32_e32 v108, v108
	v_exp_f32_e32 v113, v112
	v_mul_f32_e32 v112, 0xbfb8aa3b, v107
	v_pk_mul_f32 v[104:105], v[104:105], v[114:115]
	v_exp_f32_e32 v114, v112
	v_add_f32_e32 v109, 1.0, v109
	v_add_f32_e32 v108, 1.0, v108
	v_rcp_f32_e32 v112, v109
	v_add_f32_e32 v109, 1.0, v113
	v_rcp_f32_e32 v108, v108
	v_rcp_f32_e32 v109, v109
	v_add_f32_e32 v113, 1.0, v114
	v_rcp_f32_e32 v113, v113
	v_pk_mul_f32 v[104:105], v[104:105], v[96:97]
	v_pk_mul_f32 v[96:97], v[110:111], v[108:109]
	s_nop 0
	v_pk_mul_f32 v[102:103], v[96:97], v[102:103]
	v_pk_mul_f32 v[96:97], v[106:107], v[112:113]
	s_nop 0
	v_pk_mul_f32 v[106:107], v[96:97], v[98:99]
	v_cvt_pk_bf16_f32 v96, v100, v101
	v_cvt_pk_bf16_f32 v97, v102, v103
	v_cvt_pk_bf16_f32 v98, v104, v105
	v_cvt_pk_bf16_f32 v99, v106, v107
	v_mad_i64_i32 v[100:101], s[26:27], v116, s54, v[146:147]
	global_store_dwordx4 v[100:101], v[96:99], off nt
	v_or_b32_e32 v100, 32, v153
	s_nop 0
	v_mul_f32_e32 v96, 0xbfb8aa3b, v92
	v_mul_f32_e32 v97, 0xbfb8aa3b, v88
	v_mul_f32_e32 v98, 0xbfb8aa3b, v93
	v_exp_f32_e32 v96, v96
	v_exp_f32_e32 v97, v97
	v_exp_f32_e32 v98, v98
	v_add_f32_e32 v96, 1.0, v96
	v_add_f32_e32 v99, 1.0, v97
	v_add_f32_e32 v97, 1.0, v98
	v_rcp_f32_e32 v96, v96
	v_rcp_f32_e32 v97, v97
	v_mul_f32_e32 v98, 0xbfb8aa3b, v89
	v_exp_f32_e32 v101, v98
	v_rcp_f32_e32 v98, v99
	v_pk_mul_f32 v[92:93], v[92:93], v[96:97]
	v_mul_f32_e32 v96, 0xbfb8aa3b, v95
	v_pk_mul_f32 v[84:85], v[92:93], v[84:85]
	v_add_f32_e32 v92, 1.0, v101
	v_rcp_f32_e32 v99, v92
	v_mul_f32_e32 v93, 0xbfb8aa3b, v90
	v_mul_f32_e32 v92, 0xbfb8aa3b, v94
	v_exp_f32_e32 v93, v93
	v_exp_f32_e32 v92, v92
	v_exp_f32_e32 v97, v96
	v_mul_f32_e32 v96, 0xbfb8aa3b, v91
	v_pk_mul_f32 v[88:89], v[88:89], v[98:99]
	v_exp_f32_e32 v98, v96
	v_add_f32_e32 v93, 1.0, v93
	v_add_f32_e32 v92, 1.0, v92
	v_rcp_f32_e32 v96, v93
	v_add_f32_e32 v93, 1.0, v97
	v_rcp_f32_e32 v92, v92
	v_rcp_f32_e32 v93, v93
	v_add_f32_e32 v97, 1.0, v98
	v_rcp_f32_e32 v97, v97
	v_pk_mul_f32 v[88:89], v[88:89], v[80:81]
	v_pk_mul_f32 v[80:81], v[94:95], v[92:93]
	s_nop 0
	v_pk_mul_f32 v[86:87], v[80:81], v[86:87]
	v_pk_mul_f32 v[80:81], v[90:91], v[96:97]
	s_nop 0
	v_pk_mul_f32 v[90:91], v[80:81], v[82:83]
	v_cvt_pk_bf16_f32 v80, v84, v85
	v_cvt_pk_bf16_f32 v81, v86, v87
	v_cvt_pk_bf16_f32 v82, v88, v89
	v_cvt_pk_bf16_f32 v83, v90, v91
	v_mad_i64_i32 v[84:85], s[26:27], v100, s54, v[146:147]
	global_store_dwordx4 v[84:85], v[80:83], off nt
	v_or_b32_e32 v84, 48, v153
	s_nop 0
	v_mul_f32_e32 v80, 0xbfb8aa3b, v76
	v_mul_f32_e32 v81, 0xbfb8aa3b, v72
	v_mul_f32_e32 v82, 0xbfb8aa3b, v77
	v_exp_f32_e32 v80, v80
	v_exp_f32_e32 v81, v81
	v_exp_f32_e32 v82, v82
	v_add_f32_e32 v80, 1.0, v80
	v_add_f32_e32 v83, 1.0, v81
	v_add_f32_e32 v81, 1.0, v82
	v_rcp_f32_e32 v80, v80
	v_rcp_f32_e32 v81, v81
	v_mul_f32_e32 v82, 0xbfb8aa3b, v73
	v_exp_f32_e32 v85, v82
	v_rcp_f32_e32 v82, v83
	v_pk_mul_f32 v[76:77], v[76:77], v[80:81]
	v_mul_f32_e32 v80, 0xbfb8aa3b, v79
	v_pk_mul_f32 v[68:69], v[76:77], v[68:69]
	v_add_f32_e32 v76, 1.0, v85
	v_rcp_f32_e32 v83, v76
	v_mul_f32_e32 v77, 0xbfb8aa3b, v74
; __device__ __forceinline__ unsigned pk_bf16(float lo, float hi) { const f32x2 v = {lo, hi}; return __builtin_bit_cast(unsigned, __builtin_convertvector(v, b16x2)); }
; __device__ __forceinline__ float sigmoidf_(float x) { return __builtin_amdgcn_rcpf(1.0f + __expf(-x)); }
;     __device__ __forceinline__ void row(int r, int col32, int fq, const f32x4& a00, const f32x4& a01, const f32x4& a10, const f32x4& a11) const { half(r, col32, fq, a00, a01); half(r, col32 + HALF, fq, a10, a11); }
;     __device__ __forceinline__ void row(int r, int col32, int fq, const f32x4& a00, const f32x4& a01, const f32x4& a10, const f32x4& a11) const { half(r, col32, fq, a00, a01); half(r, col32 + HALF, fq, a10, a11); }
;     __device__ __forceinline__ void row(int r, int col32, int fq, const f32x4& a00, const f32x4& a01, const f32x4& a10, const f32x4& a11) const { half(r, col32, fq, a00, a01); half(r, col32 + HALF, fq, a10, a11); }
;     __device__ __forceinline__ void row(int r, int col32, int fq, const f32x4& g0, const f32x4& g1, const f32x4& u0, const f32x4& u1) const {
;         float o[8];
; #pragma unroll
;         for (int j = 0; j < 4; ++j) { o[j] = g0[j] * sigmoidf_(g0[j]) * u0[j]; o[4 + j] = g1[j] * sigmoidf_(g1[j]) * u1[j]; }
;         u32x4 w; w.x = pk_bf16(o[0], o[1]); w.y = pk_bf16(o[2], o[3]); w.z = pk_bf16(o[4], o[5]); w.w = pk_bf16(o[6], o[7]);
;         const int pn = col32 >> 8, cin = (col32 & 255) + 8 * fq;
;         *(u32x4*)(act + (size_t)r * DFF + pn * 128 + cin) = w;
;     }
	v_mul_f32_e32 v76, 0xbfb8aa3b, v78
	v_exp_f32_e32 v77, v77
	v_exp_f32_e32 v76, v76
	v_exp_f32_e32 v81, v80
	v_mul_f32_e32 v80, 0xbfb8aa3b, v75
	v_pk_mul_f32 v[72:73], v[72:73], v[82:83]
	v_exp_f32_e32 v82, v80
	v_add_f32_e32 v77, 1.0, v77
	v_add_f32_e32 v76, 1.0, v76
	v_rcp_f32_e32 v80, v77
	v_add_f32_e32 v77, 1.0, v81
	v_rcp_f32_e32 v76, v76
	v_rcp_f32_e32 v77, v77
	v_add_f32_e32 v81, 1.0, v82
	v_rcp_f32_e32 v81, v81
	v_pk_mul_f32 v[72:73], v[72:73], v[64:65]
	v_pk_mul_f32 v[64:65], v[78:79], v[76:77]
	s_nop 0
	v_pk_mul_f32 v[70:71], v[64:65], v[70:71]
	v_pk_mul_f32 v[64:65], v[74:75], v[80:81]
	s_nop 0
	v_pk_mul_f32 v[74:75], v[64:65], v[66:67]
	v_cvt_pk_bf16_f32 v64, v68, v69
	v_cvt_pk_bf16_f32 v65, v70, v71
	v_cvt_pk_bf16_f32 v66, v72, v73
	v_cvt_pk_bf16_f32 v67, v74, v75
	v_mad_i64_i32 v[68:69], s[26:27], v84, s54, v[146:147]
	global_store_dwordx4 v[68:69], v[64:67], off nt
	v_add_u32_e32 v68, 0x80, v153
	s_nop 0
	v_mul_f32_e32 v64, 0xbfb8aa3b, v60
	v_mul_f32_e32 v65, 0xbfb8aa3b, v56
	v_mul_f32_e32 v66, 0xbfb8aa3b, v61
	v_exp_f32_e32 v64, v64
	v_exp_f32_e32 v65, v65
	v_exp_f32_e32 v66, v66
	v_add_f32_e32 v64, 1.0, v64
	v_add_f32_e32 v67, 1.0, v65
	v_add_f32_e32 v65, 1.0, v66
	v_rcp_f32_e32 v64, v64
	v_rcp_f32_e32 v65, v65
	v_mul_f32_e32 v66, 0xbfb8aa3b, v57
	v_exp_f32_e32 v69, v66
	v_rcp_f32_e32 v66, v67
	v_pk_mul_f32 v[60:61], v[60:61], v[64:65]
	v_mul_f32_e32 v64, 0xbfb8aa3b, v63
	v_pk_mul_f32 v[52:53], v[60:61], v[52:53]
	v_add_f32_e32 v60, 1.0, v69
	v_rcp_f32_e32 v67, v60
	v_mul_f32_e32 v61, 0xbfb8aa3b, v58
	v_mul_f32_e32 v60, 0xbfb8aa3b, v62
	v_exp_f32_e32 v61, v61
	v_exp_f32_e32 v60, v60
	v_exp_f32_e32 v65, v64
	v_mul_f32_e32 v64, 0xbfb8aa3b, v59
	v_pk_mul_f32 v[56:57], v[56:57], v[66:67]
	v_exp_f32_e32 v66, v64
	v_add_f32_e32 v61, 1.0, v61
	v_add_f32_e32 v60, 1.0, v60
	v_rcp_f32_e32 v64, v61
	v_add_f32_e32 v61, 1.0, v65
	v_rcp_f32_e32 v60, v60
	v_rcp_f32_e32 v61, v61
	v_add_f32_e32 v65, 1.0, v66
	v_rcp_f32_e32 v65, v65
	v_pk_mul_f32 v[56:57], v[56:57], v[48:49]
	v_pk_mul_f32 v[48:49], v[62:63], v[60:61]
	s_nop 0
	v_pk_mul_f32 v[54:55], v[48:49], v[54:55]
	v_pk_mul_f32 v[48:49], v[58:59], v[64:65]
	s_nop 0
	v_pk_mul_f32 v[58:59], v[48:49], v[50:51]
	v_cvt_pk_bf16_f32 v48, v52, v53
	v_cvt_pk_bf16_f32 v49, v54, v55
	v_cvt_pk_bf16_f32 v50, v56, v57
	v_cvt_pk_bf16_f32 v51, v58, v59
	v_mad_i64_i32 v[52:53], s[26:27], v68, s54, v[146:147]
	global_store_dwordx4 v[52:53], v[48:51], off nt
	v_add_u32_e32 v52, 0x90, v153
	s_nop 0
	v_mul_f32_e32 v48, 0xbfb8aa3b, v44
	v_mul_f32_e32 v49, 0xbfb8aa3b, v40
	v_mul_f32_e32 v50, 0xbfb8aa3b, v45
	v_exp_f32_e32 v48, v48
	v_exp_f32_e32 v49, v49
	v_exp_f32_e32 v50, v50
	v_add_f32_e32 v48, 1.0, v48
	v_add_f32_e32 v51, 1.0, v49
	v_add_f32_e32 v49, 1.0, v50
	v_rcp_f32_e32 v48, v48
	v_rcp_f32_e32 v49, v49
	v_mul_f32_e32 v50, 0xbfb8aa3b, v41
	v_exp_f32_e32 v53, v50
	v_rcp_f32_e32 v50, v51
	v_pk_mul_f32 v[44:45], v[44:45], v[48:49]
	v_mul_f32_e32 v48, 0xbfb8aa3b, v47
	v_pk_mul_f32 v[36:37], v[44:45], v[36:37]
	v_add_f32_e32 v44, 1.0, v53
	v_rcp_f32_e32 v51, v44
	v_mul_f32_e32 v45, 0xbfb8aa3b, v42
	v_mul_f32_e32 v44, 0xbfb8aa3b, v46
	v_exp_f32_e32 v45, v45
	v_exp_f32_e32 v44, v44
	v_exp_f32_e32 v49, v48
	v_mul_f32_e32 v48, 0xbfb8aa3b, v43
	v_pk_mul_f32 v[40:41], v[40:41], v[50:51]
	v_exp_f32_e32 v50, v48
	v_add_f32_e32 v45, 1.0, v45
	v_add_f32_e32 v44, 1.0, v44
	v_rcp_f32_e32 v48, v45
	v_add_f32_e32 v45, 1.0, v49
	v_rcp_f32_e32 v44, v44
	v_rcp_f32_e32 v45, v45
	v_add_f32_e32 v49, 1.0, v50
	v_rcp_f32_e32 v49, v49
	v_pk_mul_f32 v[40:41], v[40:41], v[32:33]
	v_pk_mul_f32 v[32:33], v[46:47], v[44:45]
	s_nop 0
	v_pk_mul_f32 v[38:39], v[32:33], v[38:39]
	v_pk_mul_f32 v[32:33], v[42:43], v[48:49]
	s_nop 0
	v_pk_mul_f32 v[42:43], v[32:33], v[34:35]
	v_cvt_pk_bf16_f32 v32, v36, v37
	v_cvt_pk_bf16_f32 v33, v38, v39
	v_cvt_pk_bf16_f32 v34, v40, v41
	v_cvt_pk_bf16_f32 v35, v42, v43
	v_mad_i64_i32 v[36:37], s[26:27], v52, s54, v[146:147]
	global_store_dwordx4 v[36:37], v[32:35], off nt
	v_add_u32_e32 v36, 0xa0, v153
	s_nop 0
	v_mul_f32_e32 v32, 0xbfb8aa3b, v28
	v_mul_f32_e32 v33, 0xbfb8aa3b, v24
	v_mul_f32_e32 v34, 0xbfb8aa3b, v29
	v_exp_f32_e32 v32, v32
	v_exp_f32_e32 v33, v33
	v_exp_f32_e32 v34, v34
	v_add_f32_e32 v32, 1.0, v32
	v_add_f32_e32 v35, 1.0, v33
	v_add_f32_e32 v33, 1.0, v34
	v_rcp_f32_e32 v32, v32
	v_rcp_f32_e32 v33, v33
	v_mul_f32_e32 v34, 0xbfb8aa3b, v25
	v_exp_f32_e32 v37, v34
	v_rcp_f32_e32 v34, v35
	v_pk_mul_f32 v[28:29], v[28:29], v[32:33]
	v_mul_f32_e32 v32, 0xbfb8aa3b, v31
	v_pk_mul_f32 v[20:21], v[28:29], v[20:21]
	v_add_f32_e32 v28, 1.0, v37
	v_rcp_f32_e32 v35, v28
	v_mul_f32_e32 v29, 0xbfb8aa3b, v26
	v_mul_f32_e32 v28, 0xbfb8aa3b, v30
	v_exp_f32_e32 v29, v29
	v_exp_f32_e32 v28, v28
	v_exp_f32_e32 v33, v32
	v_mul_f32_e32 v32, 0xbfb8aa3b, v27
	v_pk_mul_f32 v[24:25], v[24:25], v[34:35]
	v_exp_f32_e32 v34, v32
	v_add_f32_e32 v29, 1.0, v29
	v_add_f32_e32 v28, 1.0, v28
	v_rcp_f32_e32 v32, v29
	v_add_f32_e32 v29, 1.0, v33
	v_rcp_f32_e32 v28, v28
	v_rcp_f32_e32 v29, v29
	v_add_f32_e32 v33, 1.0, v34
	v_rcp_f32_e32 v33, v33
	v_pk_mul_f32 v[24:25], v[24:25], v[16:17]
	v_pk_mul_f32 v[16:17], v[30:31], v[28:29]
	s_nop 0
	v_pk_mul_f32 v[22:23], v[16:17], v[22:23]
	v_pk_mul_f32 v[16:17], v[26:27], v[32:33]
	s_nop 0
	v_pk_mul_f32 v[26:27], v[16:17], v[18:19]
	v_cvt_pk_bf16_f32 v16, v20, v21
	v_cvt_pk_bf16_f32 v17, v22, v23
	v_cvt_pk_bf16_f32 v18, v24, v25
	v_cvt_pk_bf16_f32 v19, v26, v27
	v_mad_i64_i32 v[20:21], s[26:27], v36, s54, v[146:147]
	global_store_dwordx4 v[20:21], v[16:19], off nt
	v_add_u32_e32 v20, 0xb0, v153
	s_nop 0
	v_mul_f32_e32 v16, 0xbfb8aa3b, v12
	v_mul_f32_e32 v17, 0xbfb8aa3b, v8
	v_mul_f32_e32 v18, 0xbfb8aa3b, v13
	v_exp_f32_e32 v16, v16
	v_exp_f32_e32 v17, v17
	v_exp_f32_e32 v18, v18
	v_add_f32_e32 v16, 1.0, v16
	v_add_f32_e32 v19, 1.0, v17
	v_add_f32_e32 v17, 1.0, v18
	v_rcp_f32_e32 v16, v16
	v_rcp_f32_e32 v17, v17
	v_mul_f32_e32 v18, 0xbfb8aa3b, v9
	v_exp_f32_e32 v21, v18
	v_rcp_f32_e32 v18, v19
	v_pk_mul_f32 v[12:13], v[12:13], v[16:17]
	v_mul_f32_e32 v16, 0xbfb8aa3b, v15
	v_pk_mul_f32 v[4:5], v[12:13], v[4:5]
	v_add_f32_e32 v12, 1.0, v21
	v_rcp_f32_e32 v19, v12
	v_mul_f32_e32 v13, 0xbfb8aa3b, v10
	v_mul_f32_e32 v12, 0xbfb8aa3b, v14
	v_exp_f32_e32 v13, v13
	v_exp_f32_e32 v12, v12
	v_exp_f32_e32 v17, v16
	v_mul_f32_e32 v16, 0xbfb8aa3b, v11
	v_pk_mul_f32 v[8:9], v[8:9], v[18:19]
	v_exp_f32_e32 v18, v16
	v_add_f32_e32 v13, 1.0, v13
	v_add_f32_e32 v12, 1.0, v12
	v_rcp_f32_e32 v16, v13
	v_add_f32_e32 v13, 1.0, v17
	v_rcp_f32_e32 v12, v12
	v_rcp_f32_e32 v13, v13
	v_add_f32_e32 v17, 1.0, v18
	v_rcp_f32_e32 v17, v17
	v_pk_mul_f32 v[8:9], v[8:9], v[0:1]
	v_pk_mul_f32 v[0:1], v[14:15], v[12:13]
	s_nop 0
	v_pk_mul_f32 v[6:7], v[0:1], v[6:7]
	v_pk_mul_f32 v[0:1], v[10:11], v[16:17]
	s_nop 0
	v_pk_mul_f32 v[10:11], v[0:1], v[2:3]
	v_cvt_pk_bf16_f32 v0, v4, v5
	v_cvt_pk_bf16_f32 v1, v6, v7
	v_cvt_pk_bf16_f32 v2, v8, v9
	v_cvt_pk_bf16_f32 v3, v10, v11
	v_mad_i64_i32 v[4:5], s[26:27], v20, s54, v[146:147]
	global_store_dwordx4 v[4:5], v[0:3], off nt
	s_cbranch_vccnz .LBB0_1242
; #define PG8_BAR __builtin_amdgcn_s_barrier()
;     ...
;         if (!has_next) break;
; #pragma unroll
;         for (int a = 0; a < 2; ++a)
; #pragma unroll
;             for (int b = 0; b < 2; ++b)
; #pragma unroll
;                 for (int m = 0; m < 4; ++m)
; #pragma unroll
;                     for (int n = 0; n < 2; ++n) acc[a][b][m][n] = (f32x4){0.f, 0.f, 0.f, 0.f};
;         cur = nxt; cA = nA; cB = nB; ++ui;
;         if (wr == 1) PG8_BAR;
;     }
	s_andn2_b64 vcc, exec, s[0:1]
	s_cbranch_vccnz .LBB0_1241
	s_barrier
	s_branch .LBB0_1241
